# GEMM K-loops: 51 LDS-DMA issues converted from 64-bit VGPR-pair addresses (one v_lshl_add_u64 each) to SGPR base + 32-bit VGPR offset form (no VALU address add in the load segments)
# speedup vs baseline: 1.0160x; 1.0160x over previous
; #define PG8_STAGE(bufoff, gbase, voff) do { _Pragma("unroll") for (int _i = 0; _i < 2; ++_i) \
;         __builtin_amdgcn_global_load_lds((const unsigned*)((const char*)(gbase) + (voff)[_i]), (PG8_LAS unsigned*)(lds + (bufoff) + ldsw + _i * 8192), 16, 0, 0); } while (0)
; #define PG8_WAIT_V(n) asm volatile("s_waitcnt vmcnt(" #n ")" ::: "memory")
; #define PG8_BAR __builtin_amdgcn_s_barrier()
; template <class Epi, class Sched, bool ALIGN_EPI = false, bool SP2 = false>
; __device__ __forceinline__ void gemm_phase(PG8_LAS unsigned char* lds, const Gemm g, const Sched& S, const Epi& E) {
;     ...
;     const unsigned ldsw = (unsigned)wid * 1024u;
;     const int aoff = lds_byte(wr * 64 + fr, fq * 8), boff = lds_byte(wc * 32 + fr, fq * 8);
;     ...
;     if constexpr (SP2) {
;         PG8_STAGE(PG8_SB(0, 0), cB, voffB); PG8_STAGE(PG8_SB(0, 1), cB + hstep, voffB); PG8_STAGE(PG8_SA(0, 0), cA, voffA); PG8_STAGE(PG8_SA(0, 1), cA + hstep, voffA);
;         if (wr == 1) PG8_BAR;
;         PG8_WAIT_V(2); PG8_BAR;
;         PG8_STAGE(PG8_SB(1, 0), cB + kstep, voffB); PG8_STAGE(PG8_SA(1, 0), cA + kstep, voffA); PG8_STAGE(PG8_SB(1, 1), cB + hstep + kstep, voffB);
;         PG8_WAIT_V(6); PG8_BAR;
.LBB0_207:
	s_and_b64 s[16:17], exec, s[18:19]
	s_mov_b32 s9, 0xfffffc
	s_cselect_b32 s54, s9, 0xffffff
	v_readlane_b32 s9, v240, 16
	s_lshl_b32 s82, s9, 7
	s_lshl_b64 s[16:17], s[82:83], 2
	v_readlane_b32 s9, v241, 39
	s_mov_b64 s[24:25], s[18:19]
	s_add_u32 s18, s9, s16
	v_readlane_b32 s9, v241, 40
	s_addc_u32 s19, s9, s17
	s_and_b64 s[16:17], exec, s[24:25]
	v_readlane_b32 s9, v241, 42
	s_cselect_b32 s21, 0, s9
	v_readlane_b32 s9, v241, 41
	s_mov_b64 s[34:35], 0x80
	s_cselect_b32 s20, 0, s9
	s_and_b32 s6, s6, 3
	s_add_i32 m0, s29, 0x18000
	v_lshl_add_u64 v[6:7], v[6:7], 0, s[34:35]
	s_lshl_b32 s9, s7, 13
	s_lshl_b32 s22, s6, 12
	s_waitcnt vmcnt(2)
	s_barrier
	global_load_lds_dwordx4 v[6:7], off
	v_lshl_add_u64 v[4:5], v[4:5], 0, s[34:35]
	s_add_i32 m0, s29, 0x1a000
	s_add_i32 s55, s29, 0x8000
	s_add_i32 s56, s29, 0xa000
	global_load_lds_dwordx4 v[4:5], off
	v_lshl_add_u64 v[0:1], v[0:1], 0, s[34:35]
	s_mov_b32 m0, s55
	s_add_u32 s16, s10, 0x40080
	global_load_lds_dwordx4 v[0:1], off
	v_lshl_add_u64 v[0:1], v[2:3], 0, s[34:35]
	s_mov_b32 m0, s56
	s_addc_u32 s17, s11, 0
	global_load_lds_dwordx4 v[0:1], off
	s_add_i32 m0, s29, 0x1c000
	global_load_lds_dwordx4 v130, s[16:17]
	s_add_i32 m0, s29, 0x1e000
	v_bfe_u32 v2, v8, 4, 2
	global_load_lds_dwordx4 v134, s[16:17]
	v_and_b32_e32 v1, 15, v8
	v_lshlrev_b32_e32 v3, 4, v2
	v_lshl_or_b32 v158, s7, 6, v1
	v_lshl_or_b32 v3, v1, 6, v3
	v_lshlrev_b32_e32 v1, 2, v1
	v_and_b32_e32 v4, 32, v1
	s_cmpk_lt_u32 s1, 0x100
	v_bitop3_b32 v5, v3, s9, v4 bitop3:0xde
	v_bitop3_b32 v159, v3, s22, v4 bitop3:0xde
	s_cselect_b64 s[16:17], -1, 0
	v_lshlrev_b32_e32 v3, 6, v2
	s_movk_i32 s1, 0x80
	s_lshl_b32 s61, s8, 3
	v_bitop3_b32 v160, v3, s1, v1 bitop3:0x36
	v_cvt_f32_ubyte0_e32 v1, s61
	v_rcp_iflag_f32_e32 v1, v1
	v_lshlrev_b32_e32 v0, 3, v2
	s_lshl_b32 s57, s6, 6
	v_cmp_lt_u32_e64 s[6:7], 1, v2
	v_mul_f32_e32 v1, 0x4f7ffffe, v1
	v_cvt_u32_f32_e32 v1, v1
	v_lshlrev_b32_e32 v154, 5, v2
	s_lshr_b32 s60, s0, 3
	v_lshlrev_b32_e32 v2, 1, v8
	v_lshl_add_u64 v[136:137], s[18:19], 0, v[154:155]
	s_and_b64 s[8:9], exec, s[24:25]
	v_and_b32_e32 v154, 32, v2
	v_lshl_add_u64 v[138:139], s[20:21], 0, v[154:155]
	s_mov_b64 s[8:9], 0x2000
	s_cselect_b32 s62, 8, 5
	v_lshl_add_u64 v[140:141], v[138:139], 0, s[8:9]
	s_sub_i32 s8, 0, s61
	v_readfirstlane_b32 s9, v1
	s_waitcnt vmcnt(6)
	s_mul_i32 s8, s8, s9
	s_mul_hi_u32 s8, s9, s8
	s_mov_b32 s13, 0
	s_mov_b32 s1, s83
	s_add_i32 s63, s9, s8
	v_add_u32_e32 v161, 0, v5
	v_lshlrev_b32_e32 v154, 1, v0
	s_mov_b32 s77, 0x800000
	s_barrier
	s_branch .LBB0_210

; #define PG8_STAGE(bufoff, gbase, voff) do { _Pragma("unroll") for (int _i = 0; _i < 2; ++_i) \
;         __builtin_amdgcn_global_load_lds((const unsigned*)((const char*)(gbase) + (voff)[_i]), (PG8_LAS unsigned*)(lds + (bufoff) + ldsw + _i * 8192), 16, 0, 0); } while (0)
; #define PG8_LDA(dst, b, h) do { _Pragma("unroll") for (int m = 0; m < 4; ++m) _Pragma("unroll") for (int k = 0; k < 2; ++k) dst[m][k] = *(const PG8_LAS bf16x8*)(lds + PG8_SA(b, h) + aoff + m * 2048 + k * 1024); } while (0)
; #define PG8_LDB(dst, b, h) do { _Pragma("unroll") for (int n = 0; n < 2; ++n) _Pragma("unroll") for (int k = 0; k < 2; ++k) dst[n][k] = *(const PG8_LAS bf16x8*)(lds + PG8_SB(b, h) + boff + n * 2048 + k * 1024); } while (0)
; #define PG8_MMA(ai, bj, At, Bt) do { __builtin_amdgcn_s_setprio(1); _Pragma("unroll") for (int m = 0; m < 4; ++m) _Pragma("unroll") for (int n = 0; n < 2; ++n) _Pragma("unroll") for (int k = 0; k < 2; ++k) \
;         acc[ai][bj][m][n] = __builtin_amdgcn_mfma_f32_16x16x32_bf16(Bt[n][k], At[m][k], acc[ai][bj][m][n], 0, 0, 0); __builtin_amdgcn_s_setprio(0); } while (0)
; #define PG8_WAIT_V(n) asm volatile("s_waitcnt vmcnt(" #n ")" ::: "memory")
; #define PG8_WAIT_L(n) asm volatile("s_waitcnt lgkmcnt(" #n ")" ::: "memory")
; #define PG8_BAR __builtin_amdgcn_s_barrier()
; template <class Epi, class Sched, bool ALIGN_EPI = false, bool SP2 = false>
; __device__ __forceinline__ void gemm_phase(PG8_LAS unsigned char* lds, const Gemm g, const Sched& S, const Epi& E) {
;     ...
;             const char* a1 = cA + (size_t)(t + 1) * kstep;
;             const char* a2 = last ? nA : cA + (size_t)(t + 2) * kstep; const char* b2 = last ? nB : cB + (size_t)(t + 2) * kstep;
;             const char* a3 = a2 + (last ? knext : kstep); const char* b3 = b2 + (last ? knext : kstep);
;             if (last && has_next) S.a_ready(nxt);
;             if constexpr (SP2) {
;             PG8_LDB(B0, 0, 0); PG8_LDB(B1, 0, 1); PG8_SCHED; PG8_LDA(At, 0, 0); PG8_STAGE(PG8_SA(1, 1), a1 + hstep, voffA);
;             PG8_WAIT_V(8); PG8_WAIT_L(0); PG8_BAR; PG8_MMA(0, 0, At, B0); PG8_MMA(0, 1, At, B1); PG8_BAR; PG8_SCHED;
;             PG8_LDA(At, 0, 1); PG8_STAGE(PG8_SB(0, 0), b2, voffB); PG8_STAGE(PG8_SB(0, 1), b2 + hstep, voffB); PG8_STAGE(PG8_SA(0, 0), a2, voffA);
;             PG8_WAIT_V(8); PG8_WAIT_L(0); PG8_BAR; PG8_MMA(1, 0, At, B0); PG8_MMA(1, 1, At, B1); PG8_BAR; PG8_SCHED;
.LBB0_213:
	s_or_b32 s21, s13, 1
	s_mul_i32 s46, s35, s21
	s_mul_hi_u32 s47, s34, s21
	s_add_i32 s47, s47, s46
	s_mul_i32 s21, s34, s21
	s_add_u32 s21, s30, s21
	s_addc_u32 s59, s31, s47
	s_add_u32 s46, s44, s42
	s_addc_u32 s47, s45, s43
	s_add_i32 s66, 0, 0x10000
	v_add_u32_e32 v150, s66, v159
	s_add_i32 s76, 0, 0x14000
	ds_read_b128 v[142:145], v150
	ds_read_b128 v[146:149], v150 offset:1024
	ds_read_b128 v[162:165], v150 offset:2048
	ds_read_b128 v[166:169], v150 offset:3072
	v_add_u32_e32 v150, s76, v159
	ds_read_b128 v[170:173], v150
	ds_read_b128 v[174:177], v150 offset:1024
	ds_read_b128 v[178:181], v150 offset:2048
	ds_read_b128 v[182:185], v150 offset:3072
	s_add_u32 s68, s21, 0x40000
	s_addc_u32 s69, s59, 0
	s_add_i32 m0, s29, 0xc000
	ds_read_b128 v[186:189], v161
	ds_read_b128 v[190:193], v161 offset:1024
	ds_read_b128 v[198:201], v161 offset:2048
	ds_read_b128 v[202:205], v161 offset:3072
	ds_read_b128 v[206:209], v161 offset:4096
	ds_read_b128 v[210:213], v161 offset:5120
	ds_read_b128 v[214:217], v161 offset:6144
	ds_read_b128 v[218:221], v161 offset:7168
	global_load_lds_dwordx4 v128, s[68:69]
	s_add_i32 m0, s29, 0xe000
	s_nop 0
	global_load_lds_dwordx4 v132, s[68:69]
	s_waitcnt vmcnt(8)
	s_waitcnt lgkmcnt(0)
	s_barrier
	s_setprio 1
	s_waitcnt lgkmcnt(0)
	v_mfma_f32_16x16x32_bf16 v[124:127], v[142:145], v[186:189], v[124:127]
	v_mfma_f32_16x16x32_bf16 v[120:123], v[162:165], v[186:189], v[120:123]
	v_mfma_f32_16x16x32_bf16 v[108:111], v[142:145], v[198:201], v[108:111]
	v_mfma_f32_16x16x32_bf16 v[104:107], v[162:165], v[198:201], v[104:107]
	v_mfma_f32_16x16x32_bf16 v[92:95], v[142:145], v[206:209], v[92:95]
	v_mfma_f32_16x16x32_bf16 v[88:91], v[162:165], v[206:209], v[88:91]
	v_mfma_f32_16x16x32_bf16 v[76:79], v[142:145], v[214:217], v[76:79]
	v_mfma_f32_16x16x32_bf16 v[72:75], v[162:165], v[214:217], v[72:75]
	v_mfma_f32_16x16x32_bf16 v[124:127], v[146:149], v[190:193], v[124:127]
	v_mfma_f32_16x16x32_bf16 v[120:123], v[166:169], v[190:193], v[120:123]
	v_mfma_f32_16x16x32_bf16 v[108:111], v[146:149], v[202:205], v[108:111]
	v_mfma_f32_16x16x32_bf16 v[104:107], v[166:169], v[202:205], v[104:107]
	v_mfma_f32_16x16x32_bf16 v[92:95], v[146:149], v[210:213], v[92:95]
	v_mfma_f32_16x16x32_bf16 v[88:91], v[166:169], v[210:213], v[88:91]
	v_mfma_f32_16x16x32_bf16 v[76:79], v[146:149], v[218:221], v[76:79]
	v_mfma_f32_16x16x32_bf16 v[72:75], v[166:169], v[218:221], v[72:75]
	s_setprio 0
	s_setprio 1
	v_mfma_f32_16x16x32_bf16 v[116:119], v[170:173], v[186:189], v[116:119]
	v_mfma_f32_16x16x32_bf16 v[112:115], v[178:181], v[186:189], v[112:115]
	v_mfma_f32_16x16x32_bf16 v[100:103], v[170:173], v[198:201], v[100:103]
	v_mfma_f32_16x16x32_bf16 v[96:99], v[178:181], v[198:201], v[96:99]
	v_mfma_f32_16x16x32_bf16 v[84:87], v[170:173], v[206:209], v[84:87]
	v_mfma_f32_16x16x32_bf16 v[80:83], v[178:181], v[206:209], v[80:83]
	v_mfma_f32_16x16x32_bf16 v[68:71], v[170:173], v[214:217], v[68:71]
	v_mfma_f32_16x16x32_bf16 v[64:67], v[178:181], v[214:217], v[64:67]
	v_mfma_f32_16x16x32_bf16 v[116:119], v[174:177], v[190:193], v[116:119]
	v_mfma_f32_16x16x32_bf16 v[112:115], v[182:185], v[190:193], v[112:115]
	v_mfma_f32_16x16x32_bf16 v[100:103], v[174:177], v[202:205], v[100:103]
	v_mfma_f32_16x16x32_bf16 v[96:99], v[182:185], v[202:205], v[96:99]
	v_mfma_f32_16x16x32_bf16 v[84:87], v[174:177], v[210:213], v[84:87]
	v_mfma_f32_16x16x32_bf16 v[80:83], v[182:185], v[210:213], v[80:83]
	v_mfma_f32_16x16x32_bf16 v[68:71], v[174:177], v[218:221], v[68:71]
	v_mfma_f32_16x16x32_bf16 v[64:67], v[182:185], v[218:221], v[64:67]
	s_setprio 0
	s_barrier
	s_add_i32 s21, s66, s50
	s_mov_b32 m0, s21
	ds_read_b128 v[186:189], v161 offset:16384
	ds_read_b128 v[190:193], v161 offset:17408
	ds_read_b128 v[198:201], v161 offset:18432
	ds_read_b128 v[202:205], v161 offset:19456
	ds_read_b128 v[206:209], v161 offset:20480
	ds_read_b128 v[210:213], v161 offset:21504
	ds_read_b128 v[214:217], v161 offset:22528
	ds_read_b128 v[218:221], v161 offset:23552
	global_load_lds_dwordx4 v130, s[40:41]
	s_add_i32 m0, s21, 0x2000
	s_add_u32 s68, s40, 0x40000
	s_addc_u32 s69, s41, 0
	s_add_i32 s21, s76, s50
	global_load_lds_dwordx4 v134, s[40:41]
	s_mov_b32 m0, s21
	s_nop 0
	global_load_lds_dwordx4 v130, s[68:69]
	s_add_i32 m0, s21, 0x2000
	s_nop 0
	global_load_lds_dwordx4 v134, s[68:69]
	s_mov_b32 m0, s29
	s_nop 0
	global_load_lds_dwordx4 v128, s[44:45]
	s_mov_b32 m0, s51
	s_nop 0
	global_load_lds_dwordx4 v132, s[44:45]
	s_waitcnt vmcnt(8)
	s_waitcnt lgkmcnt(0)
	s_barrier
; #define PG8_STAGE(bufoff, gbase, voff) do { _Pragma("unroll") for (int _i = 0; _i < 2; ++_i) \
;         __builtin_amdgcn_global_load_lds((const unsigned*)((const char*)(gbase) + (voff)[_i]), (PG8_LAS unsigned*)(lds + (bufoff) + ldsw + _i * 8192), 16, 0, 0); } while (0)
; #define PG8_LDA(dst, b, h) do { _Pragma("unroll") for (int m = 0; m < 4; ++m) _Pragma("unroll") for (int k = 0; k < 2; ++k) dst[m][k] = *(const PG8_LAS bf16x8*)(lds + PG8_SA(b, h) + aoff + m * 2048 + k * 1024); } while (0)
; #define PG8_LDB(dst, b, h) do { _Pragma("unroll") for (int n = 0; n < 2; ++n) _Pragma("unroll") for (int k = 0; k < 2; ++k) dst[n][k] = *(const PG8_LAS bf16x8*)(lds + PG8_SB(b, h) + boff + n * 2048 + k * 1024); } while (0)
; #define PG8_MMA(ai, bj, At, Bt) do { __builtin_amdgcn_s_setprio(1); _Pragma("unroll") for (int m = 0; m < 4; ++m) _Pragma("unroll") for (int n = 0; n < 2; ++n) _Pragma("unroll") for (int k = 0; k < 2; ++k) \
;         acc[ai][bj][m][n] = __builtin_amdgcn_mfma_f32_16x16x32_bf16(Bt[n][k], At[m][k], acc[ai][bj][m][n], 0, 0, 0); __builtin_amdgcn_s_setprio(0); } while (0)
; #define PG8_WAIT_V(n) asm volatile("s_waitcnt vmcnt(" #n ")" ::: "memory")
; #define PG8_WAIT_L(n) asm volatile("s_waitcnt lgkmcnt(" #n ")" ::: "memory")
; #define PG8_BAR __builtin_amdgcn_s_barrier()
; #define PG8_SCHED __builtin_amdgcn_sched_barrier(0)
; template <class Epi, class Sched, bool ALIGN_EPI = false, bool SP2 = false>
; __device__ __forceinline__ void gemm_phase(PG8_LAS unsigned char* lds, const Gemm g, const Sched& S, const Epi& E) {
;     ...
;             PG8_WAIT_V(8); PG8_WAIT_L(0); PG8_BAR; PG8_MMA(1, 0, At, B0); PG8_MMA(1, 1, At, B1); PG8_BAR; PG8_SCHED;
;             PG8_LDB(B0, 1, 0); PG8_LDB(B1, 1, 1); PG8_SCHED; PG8_LDA(At, 1, 0); PG8_STAGE(PG8_SA(0, 1), a2 + hstep, voffA);
;             PG8_WAIT_V(8); PG8_WAIT_L(0); PG8_BAR; PG8_MMA(0, 0, At, B0); PG8_MMA(0, 1, At, B1); PG8_BAR; PG8_SCHED;
	s_setprio 1
	s_waitcnt lgkmcnt(0)
	v_mfma_f32_16x16x32_bf16 v[60:63], v[142:145], v[186:189], v[60:63]
	v_mfma_f32_16x16x32_bf16 v[56:59], v[162:165], v[186:189], v[56:59]
	v_mfma_f32_16x16x32_bf16 v[44:47], v[142:145], v[198:201], v[44:47]
	v_mfma_f32_16x16x32_bf16 v[40:43], v[162:165], v[198:201], v[40:43]
	v_mfma_f32_16x16x32_bf16 v[28:31], v[142:145], v[206:209], v[28:31]
	v_mfma_f32_16x16x32_bf16 v[24:27], v[162:165], v[206:209], v[24:27]
	v_mfma_f32_16x16x32_bf16 v[12:15], v[142:145], v[214:217], v[12:15]
	v_mfma_f32_16x16x32_bf16 v[8:11], v[162:165], v[214:217], v[8:11]
	v_mfma_f32_16x16x32_bf16 v[60:63], v[146:149], v[190:193], v[60:63]
	v_mfma_f32_16x16x32_bf16 v[56:59], v[166:169], v[190:193], v[56:59]
	v_mfma_f32_16x16x32_bf16 v[44:47], v[146:149], v[202:205], v[44:47]
	v_mfma_f32_16x16x32_bf16 v[40:43], v[166:169], v[202:205], v[40:43]
	v_mfma_f32_16x16x32_bf16 v[28:31], v[146:149], v[210:213], v[28:31]
	v_mfma_f32_16x16x32_bf16 v[24:27], v[166:169], v[210:213], v[24:27]
	v_mfma_f32_16x16x32_bf16 v[12:15], v[146:149], v[218:221], v[12:15]
	v_mfma_f32_16x16x32_bf16 v[8:11], v[166:169], v[218:221], v[8:11]
	s_setprio 0
	s_setprio 1
	v_mfma_f32_16x16x32_bf16 v[52:55], v[170:173], v[186:189], v[52:55]
	v_mfma_f32_16x16x32_bf16 v[48:51], v[178:181], v[186:189], v[48:51]
	v_mfma_f32_16x16x32_bf16 v[36:39], v[170:173], v[198:201], v[36:39]
	v_mfma_f32_16x16x32_bf16 v[32:35], v[178:181], v[198:201], v[32:35]
	v_mfma_f32_16x16x32_bf16 v[20:23], v[170:173], v[206:209], v[20:23]
	v_mfma_f32_16x16x32_bf16 v[16:19], v[178:181], v[206:209], v[16:19]
	v_mfma_f32_16x16x32_bf16 v[4:7], v[170:173], v[214:217], v[4:7]
	v_mfma_f32_16x16x32_bf16 v[0:3], v[178:181], v[214:217], v[0:3]
	v_mfma_f32_16x16x32_bf16 v[52:55], v[174:177], v[190:193], v[52:55]
	v_mfma_f32_16x16x32_bf16 v[48:51], v[182:185], v[190:193], v[48:51]
	v_mfma_f32_16x16x32_bf16 v[36:39], v[174:177], v[202:205], v[36:39]
	v_mfma_f32_16x16x32_bf16 v[32:35], v[182:185], v[202:205], v[32:35]
	v_mfma_f32_16x16x32_bf16 v[20:23], v[174:177], v[210:213], v[20:23]
	v_mfma_f32_16x16x32_bf16 v[16:19], v[182:185], v[210:213], v[16:19]
	v_mfma_f32_16x16x32_bf16 v[4:7], v[174:177], v[218:221], v[4:7]
	v_mfma_f32_16x16x32_bf16 v[0:3], v[182:185], v[218:221], v[0:3]
	s_setprio 0
	s_barrier
	s_add_i32 s21, 0, 0x18000
	v_add_u32_e32 v150, s21, v159
	s_add_i32 s59, 0, 0x1c000
	ds_read_b128 v[142:145], v150
	ds_read_b128 v[146:149], v150 offset:1024
	ds_read_b128 v[162:165], v150 offset:2048
	ds_read_b128 v[166:169], v150 offset:3072
	v_add_u32_e32 v150, s59, v159
	ds_read_b128 v[170:173], v150
	ds_read_b128 v[174:177], v150 offset:1024
	ds_read_b128 v[178:181], v150 offset:2048
	ds_read_b128 v[182:185], v150 offset:3072
	s_add_u32 s44, s44, 0x40000
	s_addc_u32 s45, s45, 0
	s_mov_b32 m0, s52
	ds_read_b128 v[186:189], v161 offset:32768
	ds_read_b128 v[190:193], v161 offset:33792
	ds_read_b128 v[198:201], v161 offset:34816
	ds_read_b128 v[202:205], v161 offset:35840
	ds_read_b128 v[206:209], v161 offset:36864
	ds_read_b128 v[210:213], v161 offset:37888
	ds_read_b128 v[214:217], v161 offset:38912
	ds_read_b128 v[218:221], v161 offset:39936
	global_load_lds_dwordx4 v128, s[44:45]
	s_mov_b32 m0, s53
	s_nop 0
	global_load_lds_dwordx4 v132, s[44:45]
	s_waitcnt vmcnt(8)
	s_waitcnt lgkmcnt(0)
	s_barrier
	s_setprio 1
	s_waitcnt lgkmcnt(0)
	v_mfma_f32_16x16x32_bf16 v[124:127], v[142:145], v[186:189], v[124:127]
	v_mfma_f32_16x16x32_bf16 v[120:123], v[162:165], v[186:189], v[120:123]
	v_mfma_f32_16x16x32_bf16 v[108:111], v[142:145], v[198:201], v[108:111]
	v_mfma_f32_16x16x32_bf16 v[104:107], v[162:165], v[198:201], v[104:107]
	v_mfma_f32_16x16x32_bf16 v[92:95], v[142:145], v[206:209], v[92:95]
	v_mfma_f32_16x16x32_bf16 v[88:91], v[162:165], v[206:209], v[88:91]
	v_mfma_f32_16x16x32_bf16 v[76:79], v[142:145], v[214:217], v[76:79]
	v_mfma_f32_16x16x32_bf16 v[72:75], v[162:165], v[214:217], v[72:75]
	v_mfma_f32_16x16x32_bf16 v[124:127], v[146:149], v[190:193], v[124:127]
	v_mfma_f32_16x16x32_bf16 v[120:123], v[166:169], v[190:193], v[120:123]
	v_mfma_f32_16x16x32_bf16 v[108:111], v[146:149], v[202:205], v[108:111]
	v_mfma_f32_16x16x32_bf16 v[104:107], v[166:169], v[202:205], v[104:107]
	v_mfma_f32_16x16x32_bf16 v[92:95], v[146:149], v[210:213], v[92:95]
	v_mfma_f32_16x16x32_bf16 v[88:91], v[166:169], v[210:213], v[88:91]
	v_mfma_f32_16x16x32_bf16 v[76:79], v[146:149], v[218:221], v[76:79]
	v_mfma_f32_16x16x32_bf16 v[72:75], v[166:169], v[218:221], v[72:75]
	s_setprio 0
	s_setprio 1
	v_mfma_f32_16x16x32_bf16 v[116:119], v[170:173], v[186:189], v[116:119]
	v_mfma_f32_16x16x32_bf16 v[112:115], v[178:181], v[186:189], v[112:115]
	v_mfma_f32_16x16x32_bf16 v[100:103], v[170:173], v[198:201], v[100:103]
	v_mfma_f32_16x16x32_bf16 v[96:99], v[178:181], v[198:201], v[96:99]
	v_mfma_f32_16x16x32_bf16 v[84:87], v[170:173], v[206:209], v[84:87]
	v_mfma_f32_16x16x32_bf16 v[80:83], v[178:181], v[206:209], v[80:83]
	v_mfma_f32_16x16x32_bf16 v[68:71], v[170:173], v[214:217], v[68:71]
	v_mfma_f32_16x16x32_bf16 v[64:67], v[178:181], v[214:217], v[64:67]
	v_mfma_f32_16x16x32_bf16 v[116:119], v[174:177], v[190:193], v[116:119]
	v_mfma_f32_16x16x32_bf16 v[112:115], v[182:185], v[190:193], v[112:115]
	v_mfma_f32_16x16x32_bf16 v[100:103], v[174:177], v[202:205], v[100:103]
	v_mfma_f32_16x16x32_bf16 v[96:99], v[182:185], v[202:205], v[96:99]
	v_mfma_f32_16x16x32_bf16 v[84:87], v[174:177], v[210:213], v[84:87]
	v_mfma_f32_16x16x32_bf16 v[80:83], v[182:185], v[210:213], v[80:83]
	v_mfma_f32_16x16x32_bf16 v[68:71], v[174:177], v[218:221], v[68:71]
	v_mfma_f32_16x16x32_bf16 v[64:67], v[182:185], v[218:221], v[64:67]
	s_setprio 0
	s_barrier
; #define PG8_STAGE(bufoff, gbase, voff) do { _Pragma("unroll") for (int _i = 0; _i < 2; ++_i) \
;         __builtin_amdgcn_global_load_lds((const unsigned*)((const char*)(gbase) + (voff)[_i]), (PG8_LAS unsigned*)(lds + (bufoff) + ldsw + _i * 8192), 16, 0, 0); } while (0)
; #define PG8_LDA(dst, b, h) do { _Pragma("unroll") for (int m = 0; m < 4; ++m) _Pragma("unroll") for (int k = 0; k < 2; ++k) dst[m][k] = *(const PG8_LAS bf16x8*)(lds + PG8_SA(b, h) + aoff + m * 2048 + k * 1024); } while (0)
; #define PG8_WAIT_V(n) asm volatile("s_waitcnt vmcnt(" #n ")" ::: "memory")
; #define PG8_WAIT_L(n) asm volatile("s_waitcnt lgkmcnt(" #n ")" ::: "memory")
; template <class Epi, class Sched, bool ALIGN_EPI = false, bool SP2 = false>
; __device__ __forceinline__ void gemm_phase(PG8_LAS unsigned char* lds, const Gemm g, const Sched& S, const Epi& E) {
;     ...
;         for (int t = 0; t < nt; t += 2) {
;             const bool last = (t == nt - 2);
;             const char* a1 = cA + (size_t)(t + 1) * kstep;
;             const char* a2 = last ? nA : cA + (size_t)(t + 2) * kstep; const char* b2 = last ? nB : cB + (size_t)(t + 2) * kstep;
;             const char* a3 = a2 + (last ? knext : kstep); const char* b3 = b2 + (last ? knext : kstep);
;             if (last && has_next) S.a_ready(nxt);
;             if constexpr (SP2) {
;             PG8_LDB(B0, 0, 0); PG8_LDB(B1, 0, 1); PG8_SCHED; PG8_LDA(At, 0, 0); PG8_STAGE(PG8_SA(1, 1), a1 + hstep, voffA);
;             PG8_WAIT_V(8); PG8_WAIT_L(0); PG8_BAR; PG8_MMA(0, 0, At, B0); PG8_MMA(0, 1, At, B1); PG8_BAR; PG8_SCHED;
;             PG8_LDA(At, 0, 1); PG8_STAGE(PG8_SB(0, 0), b2, voffB); PG8_STAGE(PG8_SB(0, 1), b2 + hstep, voffB); PG8_STAGE(PG8_SA(0, 0), a2, voffA);
;             PG8_WAIT_V(8); PG8_WAIT_L(0); PG8_BAR; PG8_MMA(1, 0, At, B0); PG8_MMA(1, 1, At, B1); PG8_BAR; PG8_SCHED;
;             PG8_LDB(B0, 1, 0); PG8_LDB(B1, 1, 1); PG8_SCHED; PG8_LDA(At, 1, 0); PG8_STAGE(PG8_SA(0, 1), a2 + hstep, voffA);
;             PG8_WAIT_V(8); PG8_WAIT_L(0); PG8_BAR; PG8_MMA(0, 0, At, B0); PG8_MMA(0, 1, At, B1); PG8_BAR; PG8_SCHED;
;             PG8_LDA(At, 1, 1); PG8_STAGE(PG8_SB(1, 0), b3, voffB); PG8_STAGE(PG8_SB(1, 1), b3 + hstep, voffB); PG8_STAGE(PG8_SA(1, 0), a3, voffA);
;             PG8_WAIT_V(8); PG8_WAIT_L(0); PG8_BAR; PG8_MMA(1, 0, At, B0); PG8_MMA(1, 1, At, B1); PG8_BAR; PG8_SCHED;
	s_add_u32 s40, s40, s42
	s_addc_u32 s41, s41, s43
	s_add_i32 s21, s21, s50
	s_mov_b32 m0, s21
	ds_read_b128 v[186:189], v161 offset:49152
	ds_read_b128 v[190:193], v161 offset:50176
	ds_read_b128 v[198:201], v161 offset:51200
	ds_read_b128 v[202:205], v161 offset:52224
	ds_read_b128 v[206:209], v161 offset:53248
	ds_read_b128 v[210:213], v161 offset:54272
	ds_read_b128 v[214:217], v161 offset:55296
	ds_read_b128 v[218:221], v161 offset:56320
	global_load_lds_dwordx4 v130, s[40:41]
	s_add_i32 m0, s21, 0x2000
	v_lshl_add_u64 v[150:151], s[40:41], 0, v[134:135]
	s_add_u32 s40, s40, 0x40000
	s_addc_u32 s41, s41, 0
	s_add_i32 s21, s59, s50
	global_load_lds_dwordx4 v[150:151], off
	s_mov_b32 m0, s21
	s_nop 0
	global_load_lds_dwordx4 v130, s[40:41]
	s_add_i32 m0, s21, 0x2000
	s_nop 0
	global_load_lds_dwordx4 v134, s[40:41]
	s_mov_b32 m0, s55
	s_nop 0
	global_load_lds_dwordx4 v128, s[46:47]
	s_mov_b32 m0, s56
	s_nop 0
	global_load_lds_dwordx4 v132, s[46:47]
	s_waitcnt vmcnt(8)
	s_waitcnt lgkmcnt(0)
	s_barrier
	s_setprio 1
	s_waitcnt lgkmcnt(0)
	v_mfma_f32_16x16x32_bf16 v[60:63], v[142:145], v[186:189], v[60:63]
	v_mfma_f32_16x16x32_bf16 v[56:59], v[162:165], v[186:189], v[56:59]
	v_mfma_f32_16x16x32_bf16 v[44:47], v[142:145], v[198:201], v[44:47]
	v_mfma_f32_16x16x32_bf16 v[40:43], v[162:165], v[198:201], v[40:43]
	v_mfma_f32_16x16x32_bf16 v[28:31], v[142:145], v[206:209], v[28:31]
	v_mfma_f32_16x16x32_bf16 v[24:27], v[162:165], v[206:209], v[24:27]
	v_mfma_f32_16x16x32_bf16 v[12:15], v[142:145], v[214:217], v[12:15]
	v_mfma_f32_16x16x32_bf16 v[8:11], v[162:165], v[214:217], v[8:11]
	v_mfma_f32_16x16x32_bf16 v[60:63], v[146:149], v[190:193], v[60:63]
	v_mfma_f32_16x16x32_bf16 v[56:59], v[166:169], v[190:193], v[56:59]
	v_mfma_f32_16x16x32_bf16 v[44:47], v[146:149], v[202:205], v[44:47]
	v_mfma_f32_16x16x32_bf16 v[40:43], v[166:169], v[202:205], v[40:43]
	v_mfma_f32_16x16x32_bf16 v[28:31], v[146:149], v[210:213], v[28:31]
	v_mfma_f32_16x16x32_bf16 v[24:27], v[166:169], v[210:213], v[24:27]
	v_mfma_f32_16x16x32_bf16 v[12:15], v[146:149], v[218:221], v[12:15]
	v_mfma_f32_16x16x32_bf16 v[8:11], v[166:169], v[218:221], v[8:11]
	s_setprio 0
	s_setprio 1
	v_mfma_f32_16x16x32_bf16 v[52:55], v[170:173], v[186:189], v[52:55]
	v_mfma_f32_16x16x32_bf16 v[48:51], v[178:181], v[186:189], v[48:51]
	v_mfma_f32_16x16x32_bf16 v[36:39], v[170:173], v[198:201], v[36:39]
	v_mfma_f32_16x16x32_bf16 v[32:35], v[178:181], v[198:201], v[32:35]
	v_mfma_f32_16x16x32_bf16 v[20:23], v[170:173], v[206:209], v[20:23]
	v_mfma_f32_16x16x32_bf16 v[16:19], v[178:181], v[206:209], v[16:19]
	v_mfma_f32_16x16x32_bf16 v[4:7], v[170:173], v[214:217], v[4:7]
	v_mfma_f32_16x16x32_bf16 v[0:3], v[178:181], v[214:217], v[0:3]
	v_mfma_f32_16x16x32_bf16 v[52:55], v[174:177], v[190:193], v[52:55]
	v_mfma_f32_16x16x32_bf16 v[48:51], v[182:185], v[190:193], v[48:51]
	v_mfma_f32_16x16x32_bf16 v[36:39], v[174:177], v[202:205], v[36:39]
	v_mfma_f32_16x16x32_bf16 v[32:35], v[182:185], v[202:205], v[32:35]
	v_mfma_f32_16x16x32_bf16 v[20:23], v[174:177], v[210:213], v[20:23]
	v_mfma_f32_16x16x32_bf16 v[16:19], v[182:185], v[210:213], v[16:19]
	v_mfma_f32_16x16x32_bf16 v[4:7], v[174:177], v[218:221], v[4:7]
	v_mfma_f32_16x16x32_bf16 v[0:3], v[182:185], v[218:221], v[0:3]
	s_setprio 0
	s_barrier
	s_cmp_gt_u32 s13, 13
	s_mov_b32 s13, s19
	s_cbranch_scc1 .LBB0_218

; #define PG8_STAGE(bufoff, gbase, voff) do { _Pragma("unroll") for (int _i = 0; _i < 2; ++_i) \
;         __builtin_amdgcn_global_load_lds((const unsigned*)((const char*)(gbase) + (voff)[_i]), (PG8_LAS unsigned*)(lds + (bufoff) + ldsw + _i * 8192), 16, 0, 0); } while (0)
; #define PG8_WAIT_V(n) asm volatile("s_waitcnt vmcnt(" #n ")" ::: "memory")
; #define PG8_BAR __builtin_amdgcn_s_barrier()
; template <class Epi, class Sched, bool ALIGN_EPI = false, bool SP2 = false>
; __device__ __forceinline__ void gemm_phase(PG8_LAS unsigned char* lds, const Gemm g, const Sched& S, const Epi& E) {
;     ...
;     if constexpr (SP2) {
;         PG8_STAGE(PG8_SB(0, 0), cB, voffB); PG8_STAGE(PG8_SB(0, 1), cB + hstep, voffB); PG8_STAGE(PG8_SA(0, 0), cA, voffA); PG8_STAGE(PG8_SA(0, 1), cA + hstep, voffA);
;         if (wr == 1) PG8_BAR;
;         PG8_WAIT_V(2); PG8_BAR;
;         PG8_STAGE(PG8_SB(1, 0), cB + kstep, voffB); PG8_STAGE(PG8_SA(1, 0), cA + kstep, voffA); PG8_STAGE(PG8_SB(1, 1), cB + hstep + kstep, voffB);
;         PG8_WAIT_V(6); PG8_BAR;
.LBB0_511:
	v_lshrrev_b32_e32 v16, 1, v11
	v_readlane_b32 s1, v240, 42
	v_and_b32_e32 v16, 24, v16
	s_add_u32 s61, s1, 0x2000
	v_readlane_b32 s1, v240, 43
	v_and_b32_e32 v15, 15, v11
	v_lshlrev_b32_e32 v17, 1, v16
	v_lshlrev_b32_e32 v11, 2, v11
	s_addc_u32 s62, s1, 0
	v_lshl_or_b32 v184, s16, 6, v15
	v_lshl_or_b32 v15, v15, 6, v17
	s_lshl_b32 s1, s16, 13
	v_and_b32_e32 v11, 32, v11
	v_bitop3_b32 v17, v15, s1, v11 bitop3:0xde
	s_lshl_b32 s1, s15, 5
	s_mov_b64 s[34:35], 0x80
	s_and_b32 s1, s1, 0x60
	s_add_i32 m0, s55, 0x18000
	v_lshl_add_u64 v[6:7], v[6:7], 0, s[34:35]
	s_lshl_b32 s9, s1, 7
	s_waitcnt vmcnt(2)
	s_barrier
	global_load_lds_dwordx4 v[6:7], off
	v_lshl_add_u64 v[4:5], v[4:5], 0, s[34:35]
	s_add_i32 m0, s55, 0x1a000
	s_add_i32 s63, s55, 0x8000
	s_add_i32 s65, s55, 0xa000
	global_load_lds_dwordx4 v[4:5], off
	v_lshl_add_u64 v[0:1], v[0:1], 0, s[34:35]
	s_mov_b32 m0, s63
	s_add_u32 s16, s40, 0x40080
	global_load_lds_dwordx4 v[0:1], off
	v_lshl_add_u64 v[0:1], v[2:3], 0, s[34:35]
	s_mov_b32 m0, s65
	s_addc_u32 s17, s41, 0
	global_load_lds_dwordx4 v[0:1], off
	s_add_i32 m0, s55, 0x1c000
	global_load_lds_dwordx4 v154, s[16:17]
	s_add_i32 m0, s55, 0x1e000
	s_cmpk_lt_u32 s14, 0x100
	global_load_lds_dwordx4 v164, s[16:17]
	v_lshlrev_b32_e32 v0, 14, v8
	v_and_b32_e32 v0, 0xffff8000, v0
	v_lshl_add_u32 v0, v9, 11, v0
	v_and_b32_e32 v1, 1, v8
	v_lshl_or_b32 v0, v1, 6, v0
	v_lshl_add_u32 v166, v10, 1, v0
	v_lshlrev_b32_e32 v0, 14, v12
	v_and_b32_e32 v0, 0xffff8000, v0
	s_waitcnt vmcnt(6)
	v_lshl_add_u32 v0, v13, 11, v0
	v_and_b32_e32 v1, 1, v12
	v_lshl_or_b32 v0, v1, 6, v0
	v_bitop3_b32 v185, v15, s9, v11 bitop3:0xde
	s_cselect_b64 s[14:15], -1, 0
	s_lshl_b32 s68, s50, 4
	s_lshl_b32 s69, s51, 6
	v_or_b32_e32 v186, s1, v16
	v_mov_b32_e32 v167, v155
	v_lshl_add_u32 v168, v14, 1, v0
	v_mov_b32_e32 v169, v155
	s_mov_b32 s1, 0
	v_add_u32_e32 v187, 0, v17
	s_barrier
	s_branch .LBB0_514

; #define PG8_STAGE(bufoff, gbase, voff) do { _Pragma("unroll") for (int _i = 0; _i < 2; ++_i) \
;         __builtin_amdgcn_global_load_lds((const unsigned*)((const char*)(gbase) + (voff)[_i]), (PG8_LAS unsigned*)(lds + (bufoff) + ldsw + _i * 8192), 16, 0, 0); } while (0)
; #define PG8_LDA(dst, b, h) do { _Pragma("unroll") for (int m = 0; m < 4; ++m) _Pragma("unroll") for (int k = 0; k < 2; ++k) dst[m][k] = *(const PG8_LAS bf16x8*)(lds + PG8_SA(b, h) + aoff + m * 2048 + k * 1024); } while (0)
; #define PG8_LDB(dst, b, h) do { _Pragma("unroll") for (int n = 0; n < 2; ++n) _Pragma("unroll") for (int k = 0; k < 2; ++k) dst[n][k] = *(const PG8_LAS bf16x8*)(lds + PG8_SB(b, h) + boff + n * 2048 + k * 1024); } while (0)
; #define PG8_MMA(ai, bj, At, Bt) do { __builtin_amdgcn_s_setprio(1); _Pragma("unroll") for (int m = 0; m < 4; ++m) _Pragma("unroll") for (int n = 0; n < 2; ++n) _Pragma("unroll") for (int k = 0; k < 2; ++k) \
;         acc[ai][bj][m][n] = __builtin_amdgcn_mfma_f32_16x16x32_bf16(Bt[n][k], At[m][k], acc[ai][bj][m][n], 0, 0, 0); __builtin_amdgcn_s_setprio(0); } while (0)
; #define PG8_WAIT_V(n) asm volatile("s_waitcnt vmcnt(" #n ")" ::: "memory")
; #define PG8_WAIT_L(n) asm volatile("s_waitcnt lgkmcnt(" #n ")" ::: "memory")
; #define PG8_BAR __builtin_amdgcn_s_barrier()
; template <class Epi, class Sched, bool ALIGN_EPI = false, bool SP2 = false>
; __device__ __forceinline__ void gemm_phase(PG8_LAS unsigned char* lds, const Gemm g, const Sched& S, const Epi& E) {
;     ...
;             const char* a1 = cA + (size_t)(t + 1) * kstep;
;             const char* a2 = last ? nA : cA + (size_t)(t + 2) * kstep; const char* b2 = last ? nB : cB + (size_t)(t + 2) * kstep;
;             const char* a3 = a2 + (last ? knext : kstep); const char* b3 = b2 + (last ? knext : kstep);
;             if (last && has_next) S.a_ready(nxt);
;             if constexpr (SP2) {
;             PG8_LDB(B0, 0, 0); PG8_LDB(B1, 0, 1); PG8_SCHED; PG8_LDA(At, 0, 0); PG8_STAGE(PG8_SA(1, 1), a1 + hstep, voffA);
;             PG8_WAIT_V(8); PG8_WAIT_L(0); PG8_BAR; PG8_MMA(0, 0, At, B0); PG8_MMA(0, 1, At, B1); PG8_BAR; PG8_SCHED;
;             PG8_LDA(At, 0, 1); PG8_STAGE(PG8_SB(0, 0), b2, voffB); PG8_STAGE(PG8_SB(0, 1), b2 + hstep, voffB); PG8_STAGE(PG8_SA(0, 0), a2, voffA);
;             PG8_WAIT_V(8); PG8_WAIT_L(0); PG8_BAR; PG8_MMA(1, 0, At, B0); PG8_MMA(1, 1, At, B1); PG8_BAR; PG8_SCHED;
.LBB0_531:
	s_add_i32 s59, s59, 2
	s_add_u32 s48, s46, s44
	s_addc_u32 s49, s47, s45
	s_add_i32 s66, 0, 0x10000
	s_add_i32 s92, 0, 0x14000
	v_add_u32_e32 v144, s66, v185
	v_add_u32_e32 v178, s92, v185
	ds_read_b128 v[100:103], v144
	ds_read_b128 v[104:107], v144 offset:1024
	ds_read_b128 v[112:115], v144 offset:2048
	ds_read_b128 v[144:147], v144 offset:3072
	ds_read_b128 v[148:151], v178
	ds_read_b128 v[170:173], v178 offset:1024
	ds_read_b128 v[174:177], v178 offset:2048
	ds_read_b128 v[178:181], v178 offset:3072
	v_lshl_add_u64 v[182:183], v[92:93], 0, s[40:41]
	s_add_i32 m0, s55, 0xc000
	ds_read_b128 v[188:191], v187
	ds_read_b128 v[198:201], v187 offset:1024
	ds_read_b128 v[202:205], v187 offset:2048
	ds_read_b128 v[206:209], v187 offset:3072
	ds_read_b128 v[210:213], v187 offset:4096
	ds_read_b128 v[214:217], v187 offset:5120
	ds_read_b128 v[218:221], v187 offset:6144
	ds_read_b128 v[222:225], v187 offset:7168
	global_load_lds_dwordx4 v[182:183], off
	v_lshl_add_u64 v[182:183], v[94:95], 0, s[40:41]
	s_add_i32 m0, s55, 0xe000
	s_nop 0
	global_load_lds_dwordx4 v[182:183], off
	s_waitcnt vmcnt(8)
	s_waitcnt lgkmcnt(0)
	s_barrier
	s_setprio 1
	s_waitcnt lgkmcnt(0)
	v_mfma_f32_16x16x32_bf16 v[140:143], v[100:103], v[188:191], v[140:143]
	v_mfma_f32_16x16x32_bf16 v[136:139], v[112:115], v[188:191], v[136:139]
	v_mfma_f32_16x16x32_bf16 v[124:127], v[100:103], v[202:205], v[124:127]
	v_mfma_f32_16x16x32_bf16 v[120:123], v[112:115], v[202:205], v[120:123]
	v_mfma_f32_16x16x32_bf16 v[96:99], v[100:103], v[210:213], v[96:99]
	v_mfma_f32_16x16x32_bf16 v[88:91], v[112:115], v[210:213], v[88:91]
	v_mfma_f32_16x16x32_bf16 v[76:79], v[100:103], v[218:221], v[76:79]
	v_mfma_f32_16x16x32_bf16 v[72:75], v[112:115], v[218:221], v[72:75]
	v_mfma_f32_16x16x32_bf16 v[140:143], v[104:107], v[198:201], v[140:143]
	v_mfma_f32_16x16x32_bf16 v[136:139], v[144:147], v[198:201], v[136:139]
	v_mfma_f32_16x16x32_bf16 v[124:127], v[104:107], v[206:209], v[124:127]
	v_mfma_f32_16x16x32_bf16 v[120:123], v[144:147], v[206:209], v[120:123]
	v_mfma_f32_16x16x32_bf16 v[96:99], v[104:107], v[214:217], v[96:99]
	v_mfma_f32_16x16x32_bf16 v[88:91], v[144:147], v[214:217], v[88:91]
	v_mfma_f32_16x16x32_bf16 v[76:79], v[104:107], v[222:225], v[76:79]
	v_mfma_f32_16x16x32_bf16 v[72:75], v[144:147], v[222:225], v[72:75]
	s_setprio 0
	s_setprio 1
	v_mfma_f32_16x16x32_bf16 v[132:135], v[148:151], v[188:191], v[132:135]
	v_mfma_f32_16x16x32_bf16 v[128:131], v[174:177], v[188:191], v[128:131]
	v_mfma_f32_16x16x32_bf16 v[116:119], v[148:151], v[202:205], v[116:119]
	v_mfma_f32_16x16x32_bf16 v[108:111], v[174:177], v[202:205], v[108:111]
	v_mfma_f32_16x16x32_bf16 v[84:87], v[148:151], v[210:213], v[84:87]
	v_mfma_f32_16x16x32_bf16 v[80:83], v[174:177], v[210:213], v[80:83]
	v_mfma_f32_16x16x32_bf16 v[68:71], v[148:151], v[218:221], v[68:71]
	v_mfma_f32_16x16x32_bf16 v[64:67], v[174:177], v[218:221], v[64:67]
	v_mfma_f32_16x16x32_bf16 v[132:135], v[170:173], v[198:201], v[132:135]
	v_mfma_f32_16x16x32_bf16 v[128:131], v[178:181], v[198:201], v[128:131]
	v_mfma_f32_16x16x32_bf16 v[116:119], v[170:173], v[206:209], v[116:119]
	v_mfma_f32_16x16x32_bf16 v[108:111], v[178:181], v[206:209], v[108:111]
	v_mfma_f32_16x16x32_bf16 v[84:87], v[170:173], v[214:217], v[84:87]
	v_mfma_f32_16x16x32_bf16 v[80:83], v[178:181], v[214:217], v[80:83]
	v_mfma_f32_16x16x32_bf16 v[68:71], v[170:173], v[222:225], v[68:71]
	v_mfma_f32_16x16x32_bf16 v[64:67], v[178:181], v[222:225], v[64:67]
	s_setprio 0
	s_barrier
	s_add_i32 s66, s66, s52
	s_mov_b32 m0, s66
	ds_read_b128 v[188:191], v187 offset:16384
	ds_read_b128 v[198:201], v187 offset:17408
	ds_read_b128 v[202:205], v187 offset:18432
	ds_read_b128 v[206:209], v187 offset:19456
	ds_read_b128 v[210:213], v187 offset:20480
	ds_read_b128 v[214:217], v187 offset:21504
	ds_read_b128 v[218:221], v187 offset:22528
	ds_read_b128 v[222:225], v187 offset:23552
	global_load_lds_dwordx4 v154, s[42:43]
	s_add_i32 m0, s66, 0x2000
	s_add_u32 s76, s42, 0x40000
	s_addc_u32 s77, s43, 0
	s_add_i32 s66, s92, s52
	global_load_lds_dwordx4 v164, s[42:43]
	s_mov_b32 m0, s66
	s_nop 0
	global_load_lds_dwordx4 v154, s[76:77]
	s_add_i32 m0, s66, 0x2000
	s_nop 0
	global_load_lds_dwordx4 v164, s[76:77]
	s_mov_b32 m0, s55
	s_nop 0
	global_load_lds_dwordx4 v160, s[46:47]
	s_mov_b32 m0, s56
	s_nop 0
	global_load_lds_dwordx4 v162, s[46:47]
	s_waitcnt vmcnt(8)
	s_waitcnt lgkmcnt(0)
	s_barrier
	s_setprio 1
	s_waitcnt lgkmcnt(0)
	v_mfma_f32_16x16x32_bf16 v[60:63], v[100:103], v[188:191], v[60:63]
	v_mfma_f32_16x16x32_bf16 v[56:59], v[112:115], v[188:191], v[56:59]
	v_mfma_f32_16x16x32_bf16 v[44:47], v[100:103], v[202:205], v[44:47]
	v_mfma_f32_16x16x32_bf16 v[40:43], v[112:115], v[202:205], v[40:43]
	v_mfma_f32_16x16x32_bf16 v[28:31], v[100:103], v[210:213], v[28:31]
	v_mfma_f32_16x16x32_bf16 v[24:27], v[112:115], v[210:213], v[24:27]
	v_mfma_f32_16x16x32_bf16 v[12:15], v[100:103], v[218:221], v[12:15]
	v_mfma_f32_16x16x32_bf16 v[8:11], v[112:115], v[218:221], v[8:11]
	v_mfma_f32_16x16x32_bf16 v[60:63], v[104:107], v[198:201], v[60:63]
	v_mfma_f32_16x16x32_bf16 v[56:59], v[144:147], v[198:201], v[56:59]
	v_mfma_f32_16x16x32_bf16 v[44:47], v[104:107], v[206:209], v[44:47]
	v_mfma_f32_16x16x32_bf16 v[40:43], v[144:147], v[206:209], v[40:43]
	v_mfma_f32_16x16x32_bf16 v[28:31], v[104:107], v[214:217], v[28:31]
	v_mfma_f32_16x16x32_bf16 v[24:27], v[144:147], v[214:217], v[24:27]
	v_mfma_f32_16x16x32_bf16 v[12:15], v[104:107], v[222:225], v[12:15]
	v_mfma_f32_16x16x32_bf16 v[8:11], v[144:147], v[222:225], v[8:11]
	s_setprio 0
	s_setprio 1
	v_mfma_f32_16x16x32_bf16 v[52:55], v[148:151], v[188:191], v[52:55]
	v_mfma_f32_16x16x32_bf16 v[48:51], v[174:177], v[188:191], v[48:51]
	v_mfma_f32_16x16x32_bf16 v[36:39], v[148:151], v[202:205], v[36:39]
	v_mfma_f32_16x16x32_bf16 v[32:35], v[174:177], v[202:205], v[32:35]
	v_mfma_f32_16x16x32_bf16 v[20:23], v[148:151], v[210:213], v[20:23]
	v_mfma_f32_16x16x32_bf16 v[16:19], v[174:177], v[210:213], v[16:19]
	v_mfma_f32_16x16x32_bf16 v[4:7], v[148:151], v[218:221], v[4:7]
	v_mfma_f32_16x16x32_bf16 v[0:3], v[174:177], v[218:221], v[0:3]
	v_mfma_f32_16x16x32_bf16 v[52:55], v[170:173], v[198:201], v[52:55]
	v_mfma_f32_16x16x32_bf16 v[48:51], v[178:181], v[198:201], v[48:51]
	v_mfma_f32_16x16x32_bf16 v[36:39], v[170:173], v[206:209], v[36:39]
	v_mfma_f32_16x16x32_bf16 v[32:35], v[178:181], v[206:209], v[32:35]
	v_mfma_f32_16x16x32_bf16 v[20:23], v[170:173], v[214:217], v[20:23]
	v_mfma_f32_16x16x32_bf16 v[16:19], v[178:181], v[214:217], v[16:19]
	v_mfma_f32_16x16x32_bf16 v[4:7], v[170:173], v[222:225], v[4:7]
	v_mfma_f32_16x16x32_bf16 v[0:3], v[178:181], v[222:225], v[0:3]
	s_setprio 0
	s_barrier
; #define PG8_STAGE(bufoff, gbase, voff) do { _Pragma("unroll") for (int _i = 0; _i < 2; ++_i) \
;         __builtin_amdgcn_global_load_lds((const unsigned*)((const char*)(gbase) + (voff)[_i]), (PG8_LAS unsigned*)(lds + (bufoff) + ldsw + _i * 8192), 16, 0, 0); } while (0)
; #define PG8_LDA(dst, b, h) do { _Pragma("unroll") for (int m = 0; m < 4; ++m) _Pragma("unroll") for (int k = 0; k < 2; ++k) dst[m][k] = *(const PG8_LAS bf16x8*)(lds + PG8_SA(b, h) + aoff + m * 2048 + k * 1024); } while (0)
; #define PG8_LDB(dst, b, h) do { _Pragma("unroll") for (int n = 0; n < 2; ++n) _Pragma("unroll") for (int k = 0; k < 2; ++k) dst[n][k] = *(const PG8_LAS bf16x8*)(lds + PG8_SB(b, h) + boff + n * 2048 + k * 1024); } while (0)
; #define PG8_MMA(ai, bj, At, Bt) do { __builtin_amdgcn_s_setprio(1); _Pragma("unroll") for (int m = 0; m < 4; ++m) _Pragma("unroll") for (int n = 0; n < 2; ++n) _Pragma("unroll") for (int k = 0; k < 2; ++k) \
;         acc[ai][bj][m][n] = __builtin_amdgcn_mfma_f32_16x16x32_bf16(Bt[n][k], At[m][k], acc[ai][bj][m][n], 0, 0, 0); __builtin_amdgcn_s_setprio(0); } while (0)
; #define PG8_WAIT_V(n) asm volatile("s_waitcnt vmcnt(" #n ")" ::: "memory")
; #define PG8_WAIT_L(n) asm volatile("s_waitcnt lgkmcnt(" #n ")" ::: "memory")
; #define PG8_BAR __builtin_amdgcn_s_barrier()
; #define PG8_SCHED __builtin_amdgcn_sched_barrier(0)
; template <class Epi, class Sched, bool ALIGN_EPI = false, bool SP2 = false>
; __device__ __forceinline__ void gemm_phase(PG8_LAS unsigned char* lds, const Gemm g, const Sched& S, const Epi& E) {
;     ...
;             PG8_WAIT_V(8); PG8_WAIT_L(0); PG8_BAR; PG8_MMA(1, 0, At, B0); PG8_MMA(1, 1, At, B1); PG8_BAR; PG8_SCHED;
;             PG8_LDB(B0, 1, 0); PG8_LDB(B1, 1, 1); PG8_SCHED; PG8_LDA(At, 1, 0); PG8_STAGE(PG8_SA(0, 1), a2 + hstep, voffA);
;             PG8_WAIT_V(8); PG8_WAIT_L(0); PG8_BAR; PG8_MMA(0, 0, At, B0); PG8_MMA(0, 1, At, B1); PG8_BAR; PG8_SCHED;
;             PG8_LDA(At, 1, 1); PG8_STAGE(PG8_SB(1, 0), b3, voffB); PG8_STAGE(PG8_SB(1, 1), b3 + hstep, voffB); PG8_STAGE(PG8_SA(1, 0), a3, voffA);
;             PG8_WAIT_V(8); PG8_WAIT_L(0); PG8_BAR; PG8_MMA(1, 0, At, B0); PG8_MMA(1, 1, At, B1); PG8_BAR; PG8_SCHED;
	s_add_i32 s66, 0, 0x18000
	s_add_i32 s76, 0, 0x1c000
	v_add_u32_e32 v144, s66, v185
	v_add_u32_e32 v178, s76, v185
	ds_read_b128 v[100:103], v144
	ds_read_b128 v[104:107], v144 offset:1024
	ds_read_b128 v[112:115], v144 offset:2048
	ds_read_b128 v[144:147], v144 offset:3072
	ds_read_b128 v[148:151], v178
	ds_read_b128 v[170:173], v178 offset:1024
	ds_read_b128 v[174:177], v178 offset:2048
	ds_read_b128 v[178:181], v178 offset:3072
	s_add_u32 s46, s46, 0x40000
	s_addc_u32 s47, s47, 0
	s_mov_b32 m0, s57
	ds_read_b128 v[188:191], v187 offset:32768
	ds_read_b128 v[198:201], v187 offset:33792
	ds_read_b128 v[202:205], v187 offset:34816
	ds_read_b128 v[206:209], v187 offset:35840
	ds_read_b128 v[210:213], v187 offset:36864
	ds_read_b128 v[214:217], v187 offset:37888
	ds_read_b128 v[218:221], v187 offset:38912
	ds_read_b128 v[222:225], v187 offset:39936
	global_load_lds_dwordx4 v160, s[46:47]
	s_mov_b32 m0, s60
	s_nop 0
	global_load_lds_dwordx4 v162, s[46:47]
	s_waitcnt vmcnt(8)
	s_waitcnt lgkmcnt(0)
	s_barrier
	s_setprio 1
	s_waitcnt lgkmcnt(0)
	v_mfma_f32_16x16x32_bf16 v[140:143], v[100:103], v[188:191], v[140:143]
	v_mfma_f32_16x16x32_bf16 v[136:139], v[112:115], v[188:191], v[136:139]
	v_mfma_f32_16x16x32_bf16 v[124:127], v[100:103], v[202:205], v[124:127]
	v_mfma_f32_16x16x32_bf16 v[120:123], v[112:115], v[202:205], v[120:123]
	v_mfma_f32_16x16x32_bf16 v[96:99], v[100:103], v[210:213], v[96:99]
	v_mfma_f32_16x16x32_bf16 v[88:91], v[112:115], v[210:213], v[88:91]
	v_mfma_f32_16x16x32_bf16 v[76:79], v[100:103], v[218:221], v[76:79]
	v_mfma_f32_16x16x32_bf16 v[72:75], v[112:115], v[218:221], v[72:75]
	v_mfma_f32_16x16x32_bf16 v[140:143], v[104:107], v[198:201], v[140:143]
	v_mfma_f32_16x16x32_bf16 v[136:139], v[144:147], v[198:201], v[136:139]
	v_mfma_f32_16x16x32_bf16 v[124:127], v[104:107], v[206:209], v[124:127]
	v_mfma_f32_16x16x32_bf16 v[120:123], v[144:147], v[206:209], v[120:123]
	v_mfma_f32_16x16x32_bf16 v[96:99], v[104:107], v[214:217], v[96:99]
	v_mfma_f32_16x16x32_bf16 v[88:91], v[144:147], v[214:217], v[88:91]
	v_mfma_f32_16x16x32_bf16 v[76:79], v[104:107], v[222:225], v[76:79]
	v_mfma_f32_16x16x32_bf16 v[72:75], v[144:147], v[222:225], v[72:75]
	s_setprio 0
	s_setprio 1
	v_mfma_f32_16x16x32_bf16 v[132:135], v[148:151], v[188:191], v[132:135]
	v_mfma_f32_16x16x32_bf16 v[128:131], v[174:177], v[188:191], v[128:131]
	v_mfma_f32_16x16x32_bf16 v[116:119], v[148:151], v[202:205], v[116:119]
	v_mfma_f32_16x16x32_bf16 v[108:111], v[174:177], v[202:205], v[108:111]
	v_mfma_f32_16x16x32_bf16 v[84:87], v[148:151], v[210:213], v[84:87]
	v_mfma_f32_16x16x32_bf16 v[80:83], v[174:177], v[210:213], v[80:83]
	v_mfma_f32_16x16x32_bf16 v[68:71], v[148:151], v[218:221], v[68:71]
	v_mfma_f32_16x16x32_bf16 v[64:67], v[174:177], v[218:221], v[64:67]
	v_mfma_f32_16x16x32_bf16 v[132:135], v[170:173], v[198:201], v[132:135]
	v_mfma_f32_16x16x32_bf16 v[128:131], v[178:181], v[198:201], v[128:131]
	v_mfma_f32_16x16x32_bf16 v[116:119], v[170:173], v[206:209], v[116:119]
	v_mfma_f32_16x16x32_bf16 v[108:111], v[178:181], v[206:209], v[108:111]
	v_mfma_f32_16x16x32_bf16 v[84:87], v[170:173], v[214:217], v[84:87]
	v_mfma_f32_16x16x32_bf16 v[80:83], v[178:181], v[214:217], v[80:83]
	v_mfma_f32_16x16x32_bf16 v[68:71], v[170:173], v[222:225], v[68:71]
	v_mfma_f32_16x16x32_bf16 v[64:67], v[178:181], v[222:225], v[64:67]
	s_setprio 0
	s_barrier
	s_add_u32 s42, s42, s44
	s_addc_u32 s43, s43, s45
	s_add_i32 s44, s66, s52
	s_mov_b32 m0, s44
	ds_read_b128 v[188:191], v187 offset:49152
	ds_read_b128 v[198:201], v187 offset:50176
	ds_read_b128 v[202:205], v187 offset:51200
	ds_read_b128 v[206:209], v187 offset:52224
	ds_read_b128 v[210:213], v187 offset:53248
	ds_read_b128 v[214:217], v187 offset:54272
	ds_read_b128 v[218:221], v187 offset:55296
	ds_read_b128 v[222:225], v187 offset:56320
	global_load_lds_dwordx4 v154, s[42:43]
	s_add_i32 m0, s44, 0x2000
	v_lshl_add_u64 v[182:183], s[42:43], 0, v[164:165]
	s_add_u32 s42, s42, 0x40000
	s_addc_u32 s43, s43, 0
	s_add_i32 s44, s76, s52
	global_load_lds_dwordx4 v[182:183], off
	s_mov_b32 m0, s44
	s_nop 0
	global_load_lds_dwordx4 v154, s[42:43]
	s_add_i32 m0, s44, 0x2000
	s_nop 0
	global_load_lds_dwordx4 v164, s[42:43]
	s_mov_b32 m0, s63
	s_nop 0
	global_load_lds_dwordx4 v160, s[48:49]
	s_mov_b32 m0, s65
	s_nop 0
	global_load_lds_dwordx4 v162, s[48:49]
	s_waitcnt vmcnt(8)
	s_waitcnt lgkmcnt(0)
	s_barrier
	s_setprio 1
	s_waitcnt lgkmcnt(0)
	v_mfma_f32_16x16x32_bf16 v[60:63], v[100:103], v[188:191], v[60:63]
	v_mfma_f32_16x16x32_bf16 v[56:59], v[112:115], v[188:191], v[56:59]
	v_mfma_f32_16x16x32_bf16 v[44:47], v[100:103], v[202:205], v[44:47]
	v_mfma_f32_16x16x32_bf16 v[40:43], v[112:115], v[202:205], v[40:43]
	v_mfma_f32_16x16x32_bf16 v[28:31], v[100:103], v[210:213], v[28:31]
	v_mfma_f32_16x16x32_bf16 v[24:27], v[112:115], v[210:213], v[24:27]
	v_mfma_f32_16x16x32_bf16 v[12:15], v[100:103], v[218:221], v[12:15]
	v_mfma_f32_16x16x32_bf16 v[8:11], v[112:115], v[218:221], v[8:11]
	v_mfma_f32_16x16x32_bf16 v[60:63], v[104:107], v[198:201], v[60:63]
	v_mfma_f32_16x16x32_bf16 v[56:59], v[144:147], v[198:201], v[56:59]
	v_mfma_f32_16x16x32_bf16 v[44:47], v[104:107], v[206:209], v[44:47]
	v_mfma_f32_16x16x32_bf16 v[40:43], v[144:147], v[206:209], v[40:43]
	v_mfma_f32_16x16x32_bf16 v[28:31], v[104:107], v[214:217], v[28:31]
	v_mfma_f32_16x16x32_bf16 v[24:27], v[144:147], v[214:217], v[24:27]
	v_mfma_f32_16x16x32_bf16 v[12:15], v[104:107], v[222:225], v[12:15]
	v_mfma_f32_16x16x32_bf16 v[8:11], v[144:147], v[222:225], v[8:11]
	s_setprio 0
	s_setprio 1
	v_mfma_f32_16x16x32_bf16 v[52:55], v[148:151], v[188:191], v[52:55]
	v_mfma_f32_16x16x32_bf16 v[48:51], v[174:177], v[188:191], v[48:51]
	v_mfma_f32_16x16x32_bf16 v[36:39], v[148:151], v[202:205], v[36:39]
	v_mfma_f32_16x16x32_bf16 v[32:35], v[174:177], v[202:205], v[32:35]
	v_mfma_f32_16x16x32_bf16 v[20:23], v[148:151], v[210:213], v[20:23]
	v_mfma_f32_16x16x32_bf16 v[16:19], v[174:177], v[210:213], v[16:19]
	v_mfma_f32_16x16x32_bf16 v[4:7], v[148:151], v[218:221], v[4:7]
	v_mfma_f32_16x16x32_bf16 v[0:3], v[174:177], v[218:221], v[0:3]
	v_mfma_f32_16x16x32_bf16 v[52:55], v[170:173], v[198:201], v[52:55]
	v_mfma_f32_16x16x32_bf16 v[48:51], v[178:181], v[198:201], v[48:51]
	v_mfma_f32_16x16x32_bf16 v[36:39], v[170:173], v[206:209], v[36:39]
	v_mfma_f32_16x16x32_bf16 v[32:35], v[178:181], v[206:209], v[32:35]
	v_mfma_f32_16x16x32_bf16 v[20:23], v[170:173], v[214:217], v[20:23]
	v_mfma_f32_16x16x32_bf16 v[16:19], v[178:181], v[214:217], v[16:19]
	v_mfma_f32_16x16x32_bf16 v[4:7], v[170:173], v[222:225], v[4:7]
	v_mfma_f32_16x16x32_bf16 v[0:3], v[178:181], v[222:225], v[0:3]
	s_setprio 0
	s_barrier
	s_add_u32 s40, s40, s38
	s_addc_u32 s41, s41, s39
	s_cmp_ge_i32 s59, s1
	s_cbranch_scc1 .LBB0_537

; #define PG8_STAGE(bufoff, gbase, voff) do { _Pragma("unroll") for (int _i = 0; _i < 2; ++_i) \
;         __builtin_amdgcn_global_load_lds((const unsigned*)((const char*)(gbase) + (voff)[_i]), (PG8_LAS unsigned*)(lds + (bufoff) + ldsw + _i * 8192), 16, 0, 0); } while (0)
; #define PG8_WAIT_V(n) asm volatile("s_waitcnt vmcnt(" #n ")" ::: "memory")
; #define PG8_BAR __builtin_amdgcn_s_barrier()
; template <class Epi, class Sched, bool ALIGN_EPI = false, bool SP2 = false>
; __device__ __forceinline__ void gemm_phase(PG8_LAS unsigned char* lds, const Gemm g, const Sched& S, const Epi& E) {
;     ...
;     if constexpr (SP2) {
;         PG8_STAGE(PG8_SB(0, 0), cB, voffB); PG8_STAGE(PG8_SB(0, 1), cB + hstep, voffB); PG8_STAGE(PG8_SA(0, 0), cA, voffA); PG8_STAGE(PG8_SA(0, 1), cA + hstep, voffA);
;         if (wr == 1) PG8_BAR;
;         PG8_WAIT_V(2); PG8_BAR;
;         PG8_STAGE(PG8_SB(1, 0), cB + kstep, voffB); PG8_STAGE(PG8_SA(1, 0), cA + kstep, voffA); PG8_STAGE(PG8_SB(1, 1), cB + hstep + kstep, voffB);
;         PG8_WAIT_V(6); PG8_BAR;
.LBB0_793:
	v_lshrrev_b32_e32 v10, 1, v0
	v_and_b32_e32 v10, 24, v10
	v_and_b32_e32 v1, 15, v0
	v_lshlrev_b32_e32 v11, 1, v10
	v_lshlrev_b32_e32 v0, 2, v0
	s_lshl_b32 s9, s9, 5
	v_lshl_or_b32 v136, s10, 6, v1
	v_lshl_or_b32 v1, v1, 6, v11
	s_lshl_b32 s10, s10, 13
	v_and_b32_e32 v0, 32, v0
	s_and_b32 s9, s9, 0x60
	v_lshl_add_u64 v[2:3], s[26:27], 0, v[154:155]
	v_mov_b32_e32 v129, v155
	v_bitop3_b32 v11, v1, s10, v0 bitop3:0xde
	s_lshl_b32 s10, s9, 7
	s_mov_b64 s[30:31], 0x80
	v_lshl_add_u64 v[4:5], s[26:27], 0, v[128:129]
	v_mov_b32_e32 v133, v155
	v_bitop3_b32 v137, v1, s10, v0 bitop3:0xde
	s_add_i32 m0, s23, 0x18000
	v_lshl_add_u64 v[0:1], v[2:3], 0, s[30:31]
	v_lshl_add_u64 v[6:7], s[28:29], 0, v[132:133]
	v_mov_b32_e32 v131, v155
	s_waitcnt vmcnt(2)
	s_barrier
	global_load_lds_dwordx4 v[0:1], off
	v_lshl_add_u64 v[0:1], v[4:5], 0, s[30:31]
	s_add_i32 m0, s23, 0x1a000
	s_add_i32 s54, s23, 0x8000
	s_add_i32 s55, s23, 0xa000
	v_lshl_add_u64 v[8:9], s[28:29], 0, v[130:131]
	global_load_lds_dwordx4 v[0:1], off
	v_lshl_add_u64 v[0:1], v[6:7], 0, s[30:31]
	s_mov_b32 m0, s54
	s_add_u32 s10, s26, 0x40080
	global_load_lds_dwordx4 v[0:1], off
	v_lshl_add_u64 v[0:1], v[8:9], 0, s[30:31]
	s_mov_b32 m0, s55
	s_addc_u32 s11, s27, 0
	global_load_lds_dwordx4 v[0:1], off
	s_add_i32 m0, s23, 0x1c000
	global_load_lds_dwordx4 v154, s[10:11]
	s_add_i32 m0, s23, 0x1e000
	s_cmpk_lt_u32 s8, 0x100
	global_load_lds_dwordx4 v128, s[10:11]
	s_waitcnt vmcnt(6)
	s_cselect_b64 s[10:11], -1, 0
	v_or_b32_e32 v138, s9, v10
	s_mov_b32 s13, 0
	v_add_u32_e32 v139, 0, v11
	s_barrier
	s_branch .LBB0_796

; #define PG8_STAGE(bufoff, gbase, voff) do { _Pragma("unroll") for (int _i = 0; _i < 2; ++_i) \
;         __builtin_amdgcn_global_load_lds((const unsigned*)((const char*)(gbase) + (voff)[_i]), (PG8_LAS unsigned*)(lds + (bufoff) + ldsw + _i * 8192), 16, 0, 0); } while (0)
; #define PG8_LDA(dst, b, h) do { _Pragma("unroll") for (int m = 0; m < 4; ++m) _Pragma("unroll") for (int k = 0; k < 2; ++k) dst[m][k] = *(const PG8_LAS bf16x8*)(lds + PG8_SA(b, h) + aoff + m * 2048 + k * 1024); } while (0)
; #define PG8_LDB(dst, b, h) do { _Pragma("unroll") for (int n = 0; n < 2; ++n) _Pragma("unroll") for (int k = 0; k < 2; ++k) dst[n][k] = *(const PG8_LAS bf16x8*)(lds + PG8_SB(b, h) + boff + n * 2048 + k * 1024); } while (0)
; #define PG8_MMA(ai, bj, At, Bt) do { __builtin_amdgcn_s_setprio(1); _Pragma("unroll") for (int m = 0; m < 4; ++m) _Pragma("unroll") for (int n = 0; n < 2; ++n) _Pragma("unroll") for (int k = 0; k < 2; ++k) \
;         acc[ai][bj][m][n] = __builtin_amdgcn_mfma_f32_16x16x32_bf16(Bt[n][k], At[m][k], acc[ai][bj][m][n], 0, 0, 0); __builtin_amdgcn_s_setprio(0); } while (0)
; #define PG8_WAIT_V(n) asm volatile("s_waitcnt vmcnt(" #n ")" ::: "memory")
; #define PG8_WAIT_L(n) asm volatile("s_waitcnt lgkmcnt(" #n ")" ::: "memory")
; #define PG8_BAR __builtin_amdgcn_s_barrier()
; template <class Epi, class Sched, bool ALIGN_EPI = false, bool SP2 = false>
; __device__ __forceinline__ void gemm_phase(PG8_LAS unsigned char* lds, const Gemm g, const Sched& S, const Epi& E) {
;     ...
;             const char* a1 = cA + (size_t)(t + 1) * kstep;
;             const char* a2 = last ? nA : cA + (size_t)(t + 2) * kstep; const char* b2 = last ? nB : cB + (size_t)(t + 2) * kstep;
;             const char* a3 = a2 + (last ? knext : kstep); const char* b3 = b2 + (last ? knext : kstep);
;             if (last && has_next) S.a_ready(nxt);
;             if constexpr (SP2) {
;             PG8_LDB(B0, 0, 0); PG8_LDB(B1, 0, 1); PG8_SCHED; PG8_LDA(At, 0, 0); PG8_STAGE(PG8_SA(1, 1), a1 + hstep, voffA);
;             PG8_WAIT_V(8); PG8_WAIT_L(0); PG8_BAR; PG8_MMA(0, 0, At, B0); PG8_MMA(0, 1, At, B1); PG8_BAR; PG8_SCHED;
;             PG8_LDA(At, 0, 1); PG8_STAGE(PG8_SB(0, 0), b2, voffB); PG8_STAGE(PG8_SB(0, 1), b2 + hstep, voffB); PG8_STAGE(PG8_SA(0, 0), a2, voffA);
;             PG8_WAIT_V(8); PG8_WAIT_L(0); PG8_BAR; PG8_MMA(1, 0, At, B0); PG8_MMA(1, 1, At, B1); PG8_BAR; PG8_SCHED;
.LBB0_799:
	s_or_b32 s44, s15, 1
	s_mul_i32 s45, s31, s44
	s_mul_hi_u32 s57, s30, s44
	s_add_i32 s57, s57, s45
	s_mul_i32 s44, s30, s44
	s_add_u32 s59, s28, s44
	s_addc_u32 s57, s29, s57
	s_add_u32 s44, s42, s40
	s_addc_u32 s45, s43, s41
	s_add_i32 s62, 0, 0x10000
	v_add_u32_e32 v134, s62, v137
	s_add_i32 s63, 0, 0x14000
	ds_read_b128 v[140:143], v134
	ds_read_b128 v[144:147], v134 offset:1024
	ds_read_b128 v[148:151], v134 offset:2048
	ds_read_b128 v[158:161], v134 offset:3072
	v_add_u32_e32 v134, s63, v137
	ds_read_b128 v[162:165], v134
	ds_read_b128 v[166:169], v134 offset:1024
	ds_read_b128 v[170:173], v134 offset:2048
	ds_read_b128 v[174:177], v134 offset:3072
	s_add_u32 s60, s59, 0x40000
	s_addc_u32 s61, s57, 0
	s_add_i32 m0, s23, 0xc000
	ds_read_b128 v[178:181], v139
	ds_read_b128 v[182:185], v139 offset:1024
	ds_read_b128 v[186:189], v139 offset:2048
	ds_read_b128 v[190:193], v139 offset:3072
	ds_read_b128 v[198:201], v139 offset:4096
	ds_read_b128 v[202:205], v139 offset:5120
	ds_read_b128 v[206:209], v139 offset:6144
	ds_read_b128 v[210:213], v139 offset:7168
	global_load_lds_dwordx4 v132, s[60:61]
	s_add_i32 m0, s23, 0xe000
	s_nop 0
	global_load_lds_dwordx4 v130, s[60:61]
	s_waitcnt vmcnt(8)
	s_waitcnt lgkmcnt(0)
	s_barrier
	s_setprio 1
	s_waitcnt lgkmcnt(0)
	v_mfma_f32_16x16x32_bf16 v[124:127], v[140:143], v[178:181], v[124:127]
	v_mfma_f32_16x16x32_bf16 v[120:123], v[148:151], v[178:181], v[120:123]
	v_mfma_f32_16x16x32_bf16 v[108:111], v[140:143], v[186:189], v[108:111]
	v_mfma_f32_16x16x32_bf16 v[104:107], v[148:151], v[186:189], v[104:107]
	v_mfma_f32_16x16x32_bf16 v[92:95], v[140:143], v[198:201], v[92:95]
	v_mfma_f32_16x16x32_bf16 v[88:91], v[148:151], v[198:201], v[88:91]
	v_mfma_f32_16x16x32_bf16 v[76:79], v[140:143], v[206:209], v[76:79]
	v_mfma_f32_16x16x32_bf16 v[72:75], v[148:151], v[206:209], v[72:75]
	v_mfma_f32_16x16x32_bf16 v[124:127], v[144:147], v[182:185], v[124:127]
	v_mfma_f32_16x16x32_bf16 v[120:123], v[158:161], v[182:185], v[120:123]
	v_mfma_f32_16x16x32_bf16 v[108:111], v[144:147], v[190:193], v[108:111]
	v_mfma_f32_16x16x32_bf16 v[104:107], v[158:161], v[190:193], v[104:107]
	v_mfma_f32_16x16x32_bf16 v[92:95], v[144:147], v[202:205], v[92:95]
	v_mfma_f32_16x16x32_bf16 v[88:91], v[158:161], v[202:205], v[88:91]
	v_mfma_f32_16x16x32_bf16 v[76:79], v[144:147], v[210:213], v[76:79]
	v_mfma_f32_16x16x32_bf16 v[72:75], v[158:161], v[210:213], v[72:75]
	s_setprio 0
	s_setprio 1
	v_mfma_f32_16x16x32_bf16 v[116:119], v[162:165], v[178:181], v[116:119]
	v_mfma_f32_16x16x32_bf16 v[112:115], v[170:173], v[178:181], v[112:115]
	v_mfma_f32_16x16x32_bf16 v[100:103], v[162:165], v[186:189], v[100:103]
	v_mfma_f32_16x16x32_bf16 v[96:99], v[170:173], v[186:189], v[96:99]
	v_mfma_f32_16x16x32_bf16 v[84:87], v[162:165], v[198:201], v[84:87]
	v_mfma_f32_16x16x32_bf16 v[80:83], v[170:173], v[198:201], v[80:83]
	v_mfma_f32_16x16x32_bf16 v[68:71], v[162:165], v[206:209], v[68:71]
	v_mfma_f32_16x16x32_bf16 v[64:67], v[170:173], v[206:209], v[64:67]
	v_mfma_f32_16x16x32_bf16 v[116:119], v[166:169], v[182:185], v[116:119]
	v_mfma_f32_16x16x32_bf16 v[112:115], v[174:177], v[182:185], v[112:115]
	v_mfma_f32_16x16x32_bf16 v[100:103], v[166:169], v[190:193], v[100:103]
	v_mfma_f32_16x16x32_bf16 v[96:99], v[174:177], v[190:193], v[96:99]
	v_mfma_f32_16x16x32_bf16 v[84:87], v[166:169], v[202:205], v[84:87]
	v_mfma_f32_16x16x32_bf16 v[80:83], v[174:177], v[202:205], v[80:83]
	v_mfma_f32_16x16x32_bf16 v[68:71], v[166:169], v[210:213], v[68:71]
	v_mfma_f32_16x16x32_bf16 v[64:67], v[174:177], v[210:213], v[64:67]
	s_setprio 0
	s_barrier
	s_add_i32 s57, s62, s51
	s_mov_b32 m0, s57
	ds_read_b128 v[178:181], v139 offset:16384
	ds_read_b128 v[182:185], v139 offset:17408
	ds_read_b128 v[186:189], v139 offset:18432
	ds_read_b128 v[190:193], v139 offset:19456
	ds_read_b128 v[198:201], v139 offset:20480
	ds_read_b128 v[202:205], v139 offset:21504
	ds_read_b128 v[206:209], v139 offset:22528
	ds_read_b128 v[210:213], v139 offset:23552
	global_load_lds_dwordx4 v154, s[38:39]
	s_add_i32 m0, s57, 0x2000
	s_add_u32 s60, s38, 0x40000
	s_addc_u32 s61, s39, 0
	s_add_i32 s57, s63, s51
	global_load_lds_dwordx4 v128, s[38:39]
	s_mov_b32 m0, s57
	s_nop 0
	global_load_lds_dwordx4 v154, s[60:61]
	s_add_i32 m0, s57, 0x2000
	s_nop 0
	global_load_lds_dwordx4 v128, s[60:61]
	s_mov_b32 m0, s23
	s_nop 0
	global_load_lds_dwordx4 v132, s[42:43]
	s_mov_b32 m0, s25
	s_nop 0
	global_load_lds_dwordx4 v130, s[42:43]
	s_waitcnt vmcnt(8)
	s_waitcnt lgkmcnt(0)
	s_barrier
; #define PG8_STAGE(bufoff, gbase, voff) do { _Pragma("unroll") for (int _i = 0; _i < 2; ++_i) \
;         __builtin_amdgcn_global_load_lds((const unsigned*)((const char*)(gbase) + (voff)[_i]), (PG8_LAS unsigned*)(lds + (bufoff) + ldsw + _i * 8192), 16, 0, 0); } while (0)
; #define PG8_LDA(dst, b, h) do { _Pragma("unroll") for (int m = 0; m < 4; ++m) _Pragma("unroll") for (int k = 0; k < 2; ++k) dst[m][k] = *(const PG8_LAS bf16x8*)(lds + PG8_SA(b, h) + aoff + m * 2048 + k * 1024); } while (0)
; #define PG8_LDB(dst, b, h) do { _Pragma("unroll") for (int n = 0; n < 2; ++n) _Pragma("unroll") for (int k = 0; k < 2; ++k) dst[n][k] = *(const PG8_LAS bf16x8*)(lds + PG8_SB(b, h) + boff + n * 2048 + k * 1024); } while (0)
; #define PG8_MMA(ai, bj, At, Bt) do { __builtin_amdgcn_s_setprio(1); _Pragma("unroll") for (int m = 0; m < 4; ++m) _Pragma("unroll") for (int n = 0; n < 2; ++n) _Pragma("unroll") for (int k = 0; k < 2; ++k) \
;         acc[ai][bj][m][n] = __builtin_amdgcn_mfma_f32_16x16x32_bf16(Bt[n][k], At[m][k], acc[ai][bj][m][n], 0, 0, 0); __builtin_amdgcn_s_setprio(0); } while (0)
; #define PG8_WAIT_V(n) asm volatile("s_waitcnt vmcnt(" #n ")" ::: "memory")
; #define PG8_WAIT_L(n) asm volatile("s_waitcnt lgkmcnt(" #n ")" ::: "memory")
; #define PG8_BAR __builtin_amdgcn_s_barrier()
; #define PG8_SCHED __builtin_amdgcn_sched_barrier(0)
; template <class Epi, class Sched, bool ALIGN_EPI = false, bool SP2 = false>
; __device__ __forceinline__ void gemm_phase(PG8_LAS unsigned char* lds, const Gemm g, const Sched& S, const Epi& E) {
;     ...
;             PG8_WAIT_V(8); PG8_WAIT_L(0); PG8_BAR; PG8_MMA(1, 0, At, B0); PG8_MMA(1, 1, At, B1); PG8_BAR; PG8_SCHED;
;             PG8_LDB(B0, 1, 0); PG8_LDB(B1, 1, 1); PG8_SCHED; PG8_LDA(At, 1, 0); PG8_STAGE(PG8_SA(0, 1), a2 + hstep, voffA);
;             PG8_WAIT_V(8); PG8_WAIT_L(0); PG8_BAR; PG8_MMA(0, 0, At, B0); PG8_MMA(0, 1, At, B1); PG8_BAR; PG8_SCHED;
	s_setprio 1
	s_waitcnt lgkmcnt(0)
	v_mfma_f32_16x16x32_bf16 v[60:63], v[140:143], v[178:181], v[60:63]
	v_mfma_f32_16x16x32_bf16 v[56:59], v[148:151], v[178:181], v[56:59]
	v_mfma_f32_16x16x32_bf16 v[44:47], v[140:143], v[186:189], v[44:47]
	v_mfma_f32_16x16x32_bf16 v[40:43], v[148:151], v[186:189], v[40:43]
	v_mfma_f32_16x16x32_bf16 v[28:31], v[140:143], v[198:201], v[28:31]
	v_mfma_f32_16x16x32_bf16 v[24:27], v[148:151], v[198:201], v[24:27]
	v_mfma_f32_16x16x32_bf16 v[12:15], v[140:143], v[206:209], v[12:15]
	v_mfma_f32_16x16x32_bf16 v[8:11], v[148:151], v[206:209], v[8:11]
	v_mfma_f32_16x16x32_bf16 v[60:63], v[144:147], v[182:185], v[60:63]
	v_mfma_f32_16x16x32_bf16 v[56:59], v[158:161], v[182:185], v[56:59]
	v_mfma_f32_16x16x32_bf16 v[44:47], v[144:147], v[190:193], v[44:47]
	v_mfma_f32_16x16x32_bf16 v[40:43], v[158:161], v[190:193], v[40:43]
	v_mfma_f32_16x16x32_bf16 v[28:31], v[144:147], v[202:205], v[28:31]
	v_mfma_f32_16x16x32_bf16 v[24:27], v[158:161], v[202:205], v[24:27]
	v_mfma_f32_16x16x32_bf16 v[12:15], v[144:147], v[210:213], v[12:15]
	v_mfma_f32_16x16x32_bf16 v[8:11], v[158:161], v[210:213], v[8:11]
	s_setprio 0
	s_setprio 1
	v_mfma_f32_16x16x32_bf16 v[52:55], v[162:165], v[178:181], v[52:55]
	v_mfma_f32_16x16x32_bf16 v[48:51], v[170:173], v[178:181], v[48:51]
	v_mfma_f32_16x16x32_bf16 v[36:39], v[162:165], v[186:189], v[36:39]
	v_mfma_f32_16x16x32_bf16 v[32:35], v[170:173], v[186:189], v[32:35]
	v_mfma_f32_16x16x32_bf16 v[20:23], v[162:165], v[198:201], v[20:23]
	v_mfma_f32_16x16x32_bf16 v[16:19], v[170:173], v[198:201], v[16:19]
	v_mfma_f32_16x16x32_bf16 v[4:7], v[162:165], v[206:209], v[4:7]
	v_mfma_f32_16x16x32_bf16 v[0:3], v[170:173], v[206:209], v[0:3]
	v_mfma_f32_16x16x32_bf16 v[52:55], v[166:169], v[182:185], v[52:55]
	v_mfma_f32_16x16x32_bf16 v[48:51], v[174:177], v[182:185], v[48:51]
	v_mfma_f32_16x16x32_bf16 v[36:39], v[166:169], v[190:193], v[36:39]
	v_mfma_f32_16x16x32_bf16 v[32:35], v[174:177], v[190:193], v[32:35]
	v_mfma_f32_16x16x32_bf16 v[20:23], v[166:169], v[202:205], v[20:23]
	v_mfma_f32_16x16x32_bf16 v[16:19], v[174:177], v[202:205], v[16:19]
	v_mfma_f32_16x16x32_bf16 v[4:7], v[166:169], v[210:213], v[4:7]
	v_mfma_f32_16x16x32_bf16 v[0:3], v[174:177], v[210:213], v[0:3]
	s_setprio 0
	s_barrier
	s_add_i32 s57, 0, 0x18000
	v_add_u32_e32 v134, s57, v137
	s_add_i32 s59, 0, 0x1c000
	ds_read_b128 v[140:143], v134
	ds_read_b128 v[144:147], v134 offset:1024
	ds_read_b128 v[148:151], v134 offset:2048
	ds_read_b128 v[158:161], v134 offset:3072
	v_add_u32_e32 v134, s59, v137
	ds_read_b128 v[162:165], v134
	ds_read_b128 v[166:169], v134 offset:1024
	ds_read_b128 v[170:173], v134 offset:2048
	ds_read_b128 v[174:177], v134 offset:3072
	s_add_u32 s42, s42, 0x40000
	s_addc_u32 s43, s43, 0
	s_mov_b32 m0, s52
	ds_read_b128 v[178:181], v139 offset:32768
	ds_read_b128 v[182:185], v139 offset:33792
	ds_read_b128 v[186:189], v139 offset:34816
	ds_read_b128 v[190:193], v139 offset:35840
	ds_read_b128 v[198:201], v139 offset:36864
	ds_read_b128 v[202:205], v139 offset:37888
	ds_read_b128 v[206:209], v139 offset:38912
	ds_read_b128 v[210:213], v139 offset:39936
	global_load_lds_dwordx4 v132, s[42:43]
	s_mov_b32 m0, s53
	s_nop 0
	global_load_lds_dwordx4 v130, s[42:43]
	s_waitcnt vmcnt(8)
	s_waitcnt lgkmcnt(0)
	s_barrier
	s_setprio 1
	s_waitcnt lgkmcnt(0)
	v_mfma_f32_16x16x32_bf16 v[124:127], v[140:143], v[178:181], v[124:127]
	v_mfma_f32_16x16x32_bf16 v[120:123], v[148:151], v[178:181], v[120:123]
	v_mfma_f32_16x16x32_bf16 v[108:111], v[140:143], v[186:189], v[108:111]
	v_mfma_f32_16x16x32_bf16 v[104:107], v[148:151], v[186:189], v[104:107]
	v_mfma_f32_16x16x32_bf16 v[92:95], v[140:143], v[198:201], v[92:95]
	v_mfma_f32_16x16x32_bf16 v[88:91], v[148:151], v[198:201], v[88:91]
	v_mfma_f32_16x16x32_bf16 v[76:79], v[140:143], v[206:209], v[76:79]
	v_mfma_f32_16x16x32_bf16 v[72:75], v[148:151], v[206:209], v[72:75]
	v_mfma_f32_16x16x32_bf16 v[124:127], v[144:147], v[182:185], v[124:127]
	v_mfma_f32_16x16x32_bf16 v[120:123], v[158:161], v[182:185], v[120:123]
	v_mfma_f32_16x16x32_bf16 v[108:111], v[144:147], v[190:193], v[108:111]
	v_mfma_f32_16x16x32_bf16 v[104:107], v[158:161], v[190:193], v[104:107]
	v_mfma_f32_16x16x32_bf16 v[92:95], v[144:147], v[202:205], v[92:95]
	v_mfma_f32_16x16x32_bf16 v[88:91], v[158:161], v[202:205], v[88:91]
	v_mfma_f32_16x16x32_bf16 v[76:79], v[144:147], v[210:213], v[76:79]
	v_mfma_f32_16x16x32_bf16 v[72:75], v[158:161], v[210:213], v[72:75]
	s_setprio 0
	s_setprio 1
	v_mfma_f32_16x16x32_bf16 v[116:119], v[162:165], v[178:181], v[116:119]
	v_mfma_f32_16x16x32_bf16 v[112:115], v[170:173], v[178:181], v[112:115]
	v_mfma_f32_16x16x32_bf16 v[100:103], v[162:165], v[186:189], v[100:103]
	v_mfma_f32_16x16x32_bf16 v[96:99], v[170:173], v[186:189], v[96:99]
	v_mfma_f32_16x16x32_bf16 v[84:87], v[162:165], v[198:201], v[84:87]
	v_mfma_f32_16x16x32_bf16 v[80:83], v[170:173], v[198:201], v[80:83]
	v_mfma_f32_16x16x32_bf16 v[68:71], v[162:165], v[206:209], v[68:71]
	v_mfma_f32_16x16x32_bf16 v[64:67], v[170:173], v[206:209], v[64:67]
	v_mfma_f32_16x16x32_bf16 v[116:119], v[166:169], v[182:185], v[116:119]
	v_mfma_f32_16x16x32_bf16 v[112:115], v[174:177], v[182:185], v[112:115]
	v_mfma_f32_16x16x32_bf16 v[100:103], v[166:169], v[190:193], v[100:103]
	v_mfma_f32_16x16x32_bf16 v[96:99], v[174:177], v[190:193], v[96:99]
	v_mfma_f32_16x16x32_bf16 v[84:87], v[166:169], v[202:205], v[84:87]
	v_mfma_f32_16x16x32_bf16 v[80:83], v[174:177], v[202:205], v[80:83]
	v_mfma_f32_16x16x32_bf16 v[68:71], v[166:169], v[210:213], v[68:71]
	v_mfma_f32_16x16x32_bf16 v[64:67], v[174:177], v[210:213], v[64:67]
	s_setprio 0
	s_barrier
; #define PG8_STAGE(bufoff, gbase, voff) do { _Pragma("unroll") for (int _i = 0; _i < 2; ++_i) \
;         __builtin_amdgcn_global_load_lds((const unsigned*)((const char*)(gbase) + (voff)[_i]), (PG8_LAS unsigned*)(lds + (bufoff) + ldsw + _i * 8192), 16, 0, 0); } while (0)
; #define PG8_LDA(dst, b, h) do { _Pragma("unroll") for (int m = 0; m < 4; ++m) _Pragma("unroll") for (int k = 0; k < 2; ++k) dst[m][k] = *(const PG8_LAS bf16x8*)(lds + PG8_SA(b, h) + aoff + m * 2048 + k * 1024); } while (0)
; #define PG8_MMA(ai, bj, At, Bt) do { __builtin_amdgcn_s_setprio(1); _Pragma("unroll") for (int m = 0; m < 4; ++m) _Pragma("unroll") for (int n = 0; n < 2; ++n) _Pragma("unroll") for (int k = 0; k < 2; ++k) \
;         acc[ai][bj][m][n] = __builtin_amdgcn_mfma_f32_16x16x32_bf16(Bt[n][k], At[m][k], acc[ai][bj][m][n], 0, 0, 0); __builtin_amdgcn_s_setprio(0); } while (0)
; #define PG8_WAIT_V(n) asm volatile("s_waitcnt vmcnt(" #n ")" ::: "memory")
; #define PG8_WAIT_L(n) asm volatile("s_waitcnt lgkmcnt(" #n ")" ::: "memory")
; #define PG8_BAR __builtin_amdgcn_s_barrier()
; #define PG8_SCHED __builtin_amdgcn_sched_barrier(0)
; template <class Epi, class Sched, bool ALIGN_EPI = false, bool SP2 = false>
; __device__ __forceinline__ void gemm_phase(PG8_LAS unsigned char* lds, const Gemm g, const Sched& S, const Epi& E) {
;     ...
;             PG8_WAIT_V(8); PG8_WAIT_L(0); PG8_BAR; PG8_MMA(0, 0, At, B0); PG8_MMA(0, 1, At, B1); PG8_BAR; PG8_SCHED;
;             PG8_LDA(At, 1, 1); PG8_STAGE(PG8_SB(1, 0), b3, voffB); PG8_STAGE(PG8_SB(1, 1), b3 + hstep, voffB); PG8_STAGE(PG8_SA(1, 0), a3, voffA);
;             PG8_WAIT_V(8); PG8_WAIT_L(0); PG8_BAR; PG8_MMA(1, 0, At, B0); PG8_MMA(1, 1, At, B1); PG8_BAR; PG8_SCHED;
	s_add_u32 s38, s38, s40
	s_addc_u32 s39, s39, s41
	s_add_i32 s40, s57, s51
	s_mov_b32 m0, s40
	ds_read_b128 v[178:181], v139 offset:49152
	ds_read_b128 v[182:185], v139 offset:50176
	ds_read_b128 v[186:189], v139 offset:51200
	ds_read_b128 v[190:193], v139 offset:52224
	ds_read_b128 v[198:201], v139 offset:53248
	ds_read_b128 v[202:205], v139 offset:54272
	ds_read_b128 v[206:209], v139 offset:55296
	ds_read_b128 v[210:213], v139 offset:56320
	global_load_lds_dwordx4 v154, s[38:39]
	s_add_i32 m0, s40, 0x2000
	v_lshl_add_u64 v[134:135], s[38:39], 0, v[128:129]
	s_add_u32 s38, s38, 0x40000
	s_addc_u32 s39, s39, 0
	s_add_i32 s40, s59, s51
	global_load_lds_dwordx4 v[134:135], off
	s_mov_b32 m0, s40
	s_nop 0
	global_load_lds_dwordx4 v154, s[38:39]
	s_add_i32 m0, s40, 0x2000
	s_nop 0
	global_load_lds_dwordx4 v128, s[38:39]
	s_mov_b32 m0, s54
	s_nop 0
	global_load_lds_dwordx4 v132, s[44:45]
	s_mov_b32 m0, s55
	s_nop 0
	global_load_lds_dwordx4 v130, s[44:45]
	s_waitcnt vmcnt(8)
	s_waitcnt lgkmcnt(0)
	s_barrier
	s_setprio 1
	s_waitcnt lgkmcnt(0)
	v_mfma_f32_16x16x32_bf16 v[60:63], v[140:143], v[178:181], v[60:63]
	v_mfma_f32_16x16x32_bf16 v[56:59], v[148:151], v[178:181], v[56:59]
	v_mfma_f32_16x16x32_bf16 v[44:47], v[140:143], v[186:189], v[44:47]
	v_mfma_f32_16x16x32_bf16 v[40:43], v[148:151], v[186:189], v[40:43]
	v_mfma_f32_16x16x32_bf16 v[28:31], v[140:143], v[198:201], v[28:31]
	v_mfma_f32_16x16x32_bf16 v[24:27], v[148:151], v[198:201], v[24:27]
	v_mfma_f32_16x16x32_bf16 v[12:15], v[140:143], v[206:209], v[12:15]
	v_mfma_f32_16x16x32_bf16 v[8:11], v[148:151], v[206:209], v[8:11]
	v_mfma_f32_16x16x32_bf16 v[60:63], v[144:147], v[182:185], v[60:63]
	v_mfma_f32_16x16x32_bf16 v[56:59], v[158:161], v[182:185], v[56:59]
	v_mfma_f32_16x16x32_bf16 v[44:47], v[144:147], v[190:193], v[44:47]
	v_mfma_f32_16x16x32_bf16 v[40:43], v[158:161], v[190:193], v[40:43]
	v_mfma_f32_16x16x32_bf16 v[28:31], v[144:147], v[202:205], v[28:31]
	v_mfma_f32_16x16x32_bf16 v[24:27], v[158:161], v[202:205], v[24:27]
	v_mfma_f32_16x16x32_bf16 v[12:15], v[144:147], v[210:213], v[12:15]
	v_mfma_f32_16x16x32_bf16 v[8:11], v[158:161], v[210:213], v[8:11]
	s_setprio 0
	s_setprio 1
	v_mfma_f32_16x16x32_bf16 v[52:55], v[162:165], v[178:181], v[52:55]
	v_mfma_f32_16x16x32_bf16 v[48:51], v[170:173], v[178:181], v[48:51]
	v_mfma_f32_16x16x32_bf16 v[36:39], v[162:165], v[186:189], v[36:39]
	v_mfma_f32_16x16x32_bf16 v[32:35], v[170:173], v[186:189], v[32:35]
	v_mfma_f32_16x16x32_bf16 v[20:23], v[162:165], v[198:201], v[20:23]
	v_mfma_f32_16x16x32_bf16 v[16:19], v[170:173], v[198:201], v[16:19]
	v_mfma_f32_16x16x32_bf16 v[4:7], v[162:165], v[206:209], v[4:7]
	v_mfma_f32_16x16x32_bf16 v[0:3], v[170:173], v[206:209], v[0:3]
	v_mfma_f32_16x16x32_bf16 v[52:55], v[166:169], v[182:185], v[52:55]
	v_mfma_f32_16x16x32_bf16 v[48:51], v[174:177], v[182:185], v[48:51]
	v_mfma_f32_16x16x32_bf16 v[36:39], v[166:169], v[190:193], v[36:39]
	v_mfma_f32_16x16x32_bf16 v[32:35], v[174:177], v[190:193], v[32:35]
	v_mfma_f32_16x16x32_bf16 v[20:23], v[166:169], v[202:205], v[20:23]
	v_mfma_f32_16x16x32_bf16 v[16:19], v[174:177], v[202:205], v[16:19]
	v_mfma_f32_16x16x32_bf16 v[4:7], v[166:169], v[210:213], v[4:7]
	v_mfma_f32_16x16x32_bf16 v[0:3], v[174:177], v[210:213], v[0:3]
	s_setprio 0
	s_barrier
	s_cmp_gt_u32 s15, 13
	s_mov_b32 s15, s13
	s_cbranch_scc1 .LBB0_804

; #define PG8_STAGE(bufoff, gbase, voff) do { _Pragma("unroll") for (int _i = 0; _i < 2; ++_i) \
;         __builtin_amdgcn_global_load_lds((const unsigned*)((const char*)(gbase) + (voff)[_i]), (PG8_LAS unsigned*)(lds + (bufoff) + ldsw + _i * 8192), 16, 0, 0); } while (0)
; #define PG8_WAIT_V(n) asm volatile("s_waitcnt vmcnt(" #n ")" ::: "memory")
; #define PG8_BAR __builtin_amdgcn_s_barrier()
; template <class Epi, class Sched, bool ALIGN_EPI = false, bool SP2 = false>
; __device__ __forceinline__ void gemm_phase(PG8_LAS unsigned char* lds, const Gemm g, const Sched& S, const Epi& E) {
;     ...
;     if constexpr (SP2) {
;         PG8_STAGE(PG8_SB(0, 0), cB, voffB); PG8_STAGE(PG8_SB(0, 1), cB + hstep, voffB); PG8_STAGE(PG8_SA(0, 0), cA, voffA); PG8_STAGE(PG8_SA(0, 1), cA + hstep, voffA);
;         if (wr == 1) PG8_BAR;
;         PG8_WAIT_V(2); PG8_BAR;
;         PG8_STAGE(PG8_SB(1, 0), cB + kstep, voffB); PG8_STAGE(PG8_SA(1, 0), cA + kstep, voffA); PG8_STAGE(PG8_SB(1, 1), cB + hstep + kstep, voffB);
;         PG8_WAIT_V(6); PG8_BAR;
.LBB0_880:
	v_lshrrev_b32_e32 v16, 1, v8
	v_readlane_b32 s1, v240, 42
	v_and_b32_e32 v16, 24, v16
	s_add_u32 s39, s1, 0x5000
	v_readlane_b32 s1, v240, 43
	v_and_b32_e32 v15, 15, v8
	v_lshlrev_b32_e32 v17, 1, v16
	v_lshlrev_b32_e32 v8, 2, v8
	s_addc_u32 s40, s1, 0
	v_lshl_or_b32 v186, s15, 6, v15
	v_lshl_or_b32 v15, v15, 6, v17
	s_lshl_b32 s1, s15, 13
	v_and_b32_e32 v8, 32, v8
	v_bitop3_b32 v17, v15, s1, v8 bitop3:0xde
	s_lshl_b32 s1, s14, 5
	s_and_b32 s1, s1, 0x60
	s_add_i32 m0, s35, 0x18000
	v_lshl_add_u64 v[6:7], v[6:7], 0, s[84:85]
	s_lshl_b32 s9, s1, 7
	s_waitcnt vmcnt(2)
	s_barrier
	global_load_lds_dwordx4 v[6:7], off
	v_lshl_add_u64 v[4:5], v[4:5], 0, s[84:85]
	s_add_i32 m0, s35, 0x1a000
	s_add_i32 s41, s35, 0x8000
	s_add_i32 s42, s35, 0xa000
	global_load_lds_dwordx4 v[4:5], off
	v_lshl_add_u64 v[0:1], v[0:1], 0, s[84:85]
	s_mov_b32 m0, s41
	s_add_u32 s14, s6, 0xfff80
	global_load_lds_dwordx4 v[0:1], off
	v_lshl_add_u64 v[0:1], v[2:3], 0, s[84:85]
	s_mov_b32 m0, s42
	s_addc_u32 s15, s7, 0
	global_load_lds_dwordx4 v[0:1], off
	s_add_i32 m0, s35, 0x1c000
	global_load_lds_dwordx4 v154, s[14:15]
	s_add_i32 m0, s35, 0x1e000
	s_cmpk_lt_u32 s18, 0x100
	global_load_lds_dwordx4 v164, s[14:15]
	v_lshlrev_b32_e32 v0, 16, v9
	v_and_b32_e32 v0, 0xfffe0000, v0
	v_lshl_add_u32 v0, v10, 13, v0
	v_and_b32_e32 v1, 1, v9
	v_lshl_or_b32 v0, v1, 6, v0
	v_lshl_add_u32 v166, v11, 1, v0
	v_lshlrev_b32_e32 v0, 16, v12
	v_and_b32_e32 v0, 0xfffe0000, v0
	s_waitcnt vmcnt(6)
	v_lshl_add_u32 v0, v13, 13, v0
	v_and_b32_e32 v1, 1, v12
	v_lshl_or_b32 v0, v1, 6, v0
	v_bitop3_b32 v187, v15, s9, v8 bitop3:0xde
	s_cselect_b64 s[14:15], -1, 0
	s_lshl_b32 s43, s28, 4
	s_lshl_b32 s44, s29, 6
	v_or_b32_e32 v188, s1, v16
	v_mov_b32_e32 v167, v155
	v_lshl_add_u32 v168, v14, 1, v0
	v_mov_b32_e32 v169, v155
	s_mov_b32 s19, 0
	v_mov_b64_e32 v[0:1], s[6:7]
	v_mov_b64_e32 v[2:3], s[16:17]
	v_add_u32_e32 v189, 0, v17
	s_barrier
	s_branch .LBB0_883
